# scan chunk start: wait only for the operands needed next (K,v,A then W) instead of the first whole step, and step 0 no longer drains all 18 prologue loads
# speedup vs baseline: 1.0037x; 1.0037x over previous
.LBB0_633:
	s_cmpk_lg_i32 s44, 0x2100
	s_cselect_b64 s[8:9], -1, 0
	v_cndmask_b32_e64 v0, 0, 1, s[8:9]
	v_cmp_ne_u32_e64 s[8:9], 1, v0
	s_and_saveexec_b64 s[34:35], s[2:3]
	s_xor_b64 s[50:51], exec, s[34:35]
	s_cbranch_execz .LBB0_636
	s_and_b64 vcc, exec, s[8:9]
	s_cbranch_vccnz .LBB0_636
	ds_read_b128 v[108:111], v53 offset:768
	ds_read_b32 v242, v65 offset:1280
	ds_read_b128 v[14:17], v53 offset:256
	ds_read_b128 v[10:13], v53
	ds_read_b128 v[18:21], v53 offset:512
	ds_read_b128 v[22:25], v53 offset:1024
	ds_read_b128 v[220:223], v53 offset:2112
	ds_read_b32 v246, v65 offset:2624
	ds_read_b128 v[122:125], v53 offset:1600
	ds_read_b128 v[118:121], v53 offset:1344
	ds_read_b128 v[134:137], v53 offset:1856
	ds_read_b128 v[230:233], v53 offset:2368
	ds_read_b128 v[224:227], v53 offset:3456
	ds_read_b32 v214, v65 offset:3968
	ds_read_b128 v[142:145], v53 offset:2944
	ds_read_b128 v[138:141], v53 offset:2688
	ds_read_b128 v[146:149], v53 offset:3200
	ds_read_b128 v[150:153], v53 offset:3712
	s_waitcnt lgkmcnt(15)
	v_pk_mul_f32 v[108:109], v[108:109], v[242:243] op_sel_hi:[1,0]
	v_pk_mul_f32 v[110:111], v[110:111], v[242:243] op_sel_hi:[1,0]
	v_pk_mul_f32 v[250:251], v[84:85], v[14:15]
	s_waitcnt lgkmcnt(14)
	v_pk_fma_f32 v[108:109], v[84:85], v[10:11], v[108:109]
	v_pk_fma_f32 v[250:251], v[86:87], v[16:17], v[250:251]
	s_nop 0
	v_add_f32_e32 v0, v250, v251
	v_pk_fma_f32 v[110:111], v[86:87], v[12:13], v[110:111]
	s_nop 0
	v_add_f32_dpp v0, v0, v0 row_ror:8 row_mask:0xf bank_mask:0xf bound_ctrl:1
	s_waitcnt lgkmcnt(6)
	v_pk_mul_f32 v[220:221], v[220:221], v[246:247] op_sel_hi:[1,0]
	v_add_f32_dpp v0, v0, v0 row_ror:4 row_mask:0xf bank_mask:0xf bound_ctrl:1
	v_pk_mul_f32 v[222:223], v[222:223], v[246:247] op_sel_hi:[1,0]
	ds_read_b128 v[236:239], v53 offset:4800
	ds_read_b32 v234, v65 offset:5312
	ds_read_b128 v[198:201], v53 offset:4288
	v_add_f32_dpp v0, v0, v0 row_ror:2 row_mask:0xf bank_mask:0xf bound_ctrl:1
	ds_read_b128 v[194:197], v53 offset:4032
	ds_read_b128 v[202:205], v53 offset:4544
	ds_read_b128 v[206:209], v53 offset:5056
	v_add_f32_dpp v0, v0, v0 row_ror:1 row_mask:0xf bank_mask:0xf bound_ctrl:1
	v_pk_fma_f32 v[84:85], v[0:1], v[18:19], v[108:109] op_sel_hi:[0,1,1]
	v_pk_fma_f32 v[86:87], v[0:1], v[20:21], v[110:111] op_sel_hi:[0,1,1]
	v_pk_mul_f32 v[250:251], v[84:85], v[122:123]
	v_pk_fma_f32 v[220:221], v[84:85], v[118:119], v[220:221]
	v_pk_fma_f32 v[250:251], v[86:87], v[124:125], v[250:251]
	v_pk_mul_f32 v[186:187], v[84:85], v[22:23]
	v_add_f32_e32 v0, v250, v251
	v_pk_fma_f32 v[222:223], v[86:87], v[120:121], v[222:223]
	v_pk_fma_f32 v[186:187], v[86:87], v[24:25], v[186:187]
	v_add_f32_dpp v0, v0, v0 row_ror:8 row_mask:0xf bank_mask:0xf bound_ctrl:1
	s_waitcnt lgkmcnt(6)
	v_pk_mul_f32 v[224:225], v[224:225], v[214:215] op_sel_hi:[1,0]
	v_add_f32_e32 v218, v186, v187
	v_add_f32_dpp v0, v0, v0 row_ror:4 row_mask:0xf bank_mask:0xf bound_ctrl:1
	v_pk_mul_f32 v[226:227], v[226:227], v[214:215] op_sel_hi:[1,0]
	ds_read_b128 v[108:111], v53 offset:6144
	ds_read_b32 v242, v65 offset:6656
	ds_read_b128 v[14:17], v53 offset:5632
	v_add_f32_dpp v0, v0, v0 row_ror:2 row_mask:0xf bank_mask:0xf bound_ctrl:1
	ds_read_b128 v[10:13], v53 offset:5376
	ds_read_b128 v[18:21], v53 offset:5888
	ds_read_b128 v[22:25], v53 offset:6400
	v_add_f32_dpp v0, v0, v0 row_ror:1 row_mask:0xf bank_mask:0xf bound_ctrl:1
	v_pk_fma_f32 v[84:85], v[0:1], v[134:135], v[220:221] op_sel_hi:[0,1,1]
	v_pk_fma_f32 v[86:87], v[0:1], v[136:137], v[222:223] op_sel_hi:[0,1,1]
	v_pk_mul_f32 v[250:251], v[84:85], v[142:143]
	v_pk_fma_f32 v[224:225], v[84:85], v[138:139], v[224:225]
	v_pk_fma_f32 v[250:251], v[86:87], v[144:145], v[250:251]
	v_pk_mul_f32 v[186:187], v[84:85], v[230:231]
	v_add_f32_e32 v0, v250, v251
	v_pk_fma_f32 v[226:227], v[86:87], v[140:141], v[226:227]
	v_pk_fma_f32 v[186:187], v[86:87], v[232:233], v[186:187]
	v_add_f32_dpp v0, v0, v0 row_ror:8 row_mask:0xf bank_mask:0xf bound_ctrl:1
	s_waitcnt lgkmcnt(6)
	v_pk_mul_f32 v[236:237], v[236:237], v[234:235] op_sel_hi:[1,0]
	v_add_f32_e32 v219, v186, v187
	v_add_f32_dpp v0, v0, v0 row_ror:4 row_mask:0xf bank_mask:0xf bound_ctrl:1
	v_pk_mul_f32 v[238:239], v[238:239], v[234:235] op_sel_hi:[1,0]
	ds_write2st64_b32 v77, v218, v219 offset0:0 offset1:4
	ds_read_b128 v[220:223], v53 offset:7488
	ds_read_b32 v246, v65 offset:8000
	ds_read_b128 v[122:125], v53 offset:6976
	v_add_f32_dpp v0, v0, v0 row_ror:2 row_mask:0xf bank_mask:0xf bound_ctrl:1
	ds_read_b128 v[118:121], v53 offset:6720
	ds_read_b128 v[134:137], v53 offset:7232
	ds_read_b128 v[230:233], v53 offset:7744
	v_add_f32_dpp v0, v0, v0 row_ror:1 row_mask:0xf bank_mask:0xf bound_ctrl:1
	v_pk_fma_f32 v[84:85], v[0:1], v[146:147], v[224:225] op_sel_hi:[0,1,1]
	v_pk_fma_f32 v[86:87], v[0:1], v[148:149], v[226:227] op_sel_hi:[0,1,1]
	v_pk_mul_f32 v[250:251], v[84:85], v[198:199]
	v_pk_fma_f32 v[236:237], v[84:85], v[194:195], v[236:237]
	v_pk_fma_f32 v[250:251], v[86:87], v[200:201], v[250:251]
	v_pk_mul_f32 v[186:187], v[84:85], v[150:151]
	v_add_f32_e32 v0, v250, v251
	v_pk_fma_f32 v[238:239], v[86:87], v[196:197], v[238:239]
	v_pk_fma_f32 v[186:187], v[86:87], v[152:153], v[186:187]
	v_add_f32_dpp v0, v0, v0 row_ror:8 row_mask:0xf bank_mask:0xf bound_ctrl:1
	s_waitcnt lgkmcnt(7)
	v_pk_mul_f32 v[108:109], v[108:109], v[242:243] op_sel_hi:[1,0]
	v_add_f32_e32 v218, v186, v187
	v_add_f32_dpp v0, v0, v0 row_ror:4 row_mask:0xf bank_mask:0xf bound_ctrl:1
	v_pk_mul_f32 v[110:111], v[110:111], v[242:243] op_sel_hi:[1,0]
	ds_read_b128 v[224:227], v53 offset:8832
	ds_read_b32 v214, v65 offset:9344
	ds_read_b128 v[142:145], v53 offset:8320
	v_add_f32_dpp v0, v0, v0 row_ror:2 row_mask:0xf bank_mask:0xf bound_ctrl:1
	ds_read_b128 v[138:141], v53 offset:8064
	ds_read_b128 v[146:149], v53 offset:8576
	ds_read_b128 v[150:153], v53 offset:9088
	v_add_f32_dpp v0, v0, v0 row_ror:1 row_mask:0xf bank_mask:0xf bound_ctrl:1
	v_pk_fma_f32 v[84:85], v[0:1], v[202:203], v[236:237] op_sel_hi:[0,1,1]
	v_pk_fma_f32 v[86:87], v[0:1], v[204:205], v[238:239] op_sel_hi:[0,1,1]
	v_pk_mul_f32 v[250:251], v[84:85], v[14:15]
	v_pk_fma_f32 v[108:109], v[84:85], v[10:11], v[108:109]
	v_pk_fma_f32 v[250:251], v[86:87], v[16:17], v[250:251]
	v_pk_mul_f32 v[186:187], v[84:85], v[206:207]
	v_add_f32_e32 v0, v250, v251
	v_pk_fma_f32 v[110:111], v[86:87], v[12:13], v[110:111]
	v_pk_fma_f32 v[186:187], v[86:87], v[208:209], v[186:187]
	v_add_f32_dpp v0, v0, v0 row_ror:8 row_mask:0xf bank_mask:0xf bound_ctrl:1
	s_waitcnt lgkmcnt(6)
	v_pk_mul_f32 v[220:221], v[220:221], v[246:247] op_sel_hi:[1,0]
	v_add_f32_e32 v219, v186, v187
	v_add_f32_dpp v0, v0, v0 row_ror:4 row_mask:0xf bank_mask:0xf bound_ctrl:1
	v_pk_mul_f32 v[222:223], v[222:223], v[246:247] op_sel_hi:[1,0]
	ds_write2st64_b32 v77, v218, v219 offset0:8 offset1:12
	ds_read_b128 v[236:239], v53 offset:10176
	ds_read_b32 v234, v65 offset:10688
	ds_read_b128 v[198:201], v53 offset:9664
	v_add_f32_dpp v0, v0, v0 row_ror:2 row_mask:0xf bank_mask:0xf bound_ctrl:1
	ds_read_b128 v[194:197], v53 offset:9408
	ds_read_b128 v[202:205], v53 offset:9920
	ds_read_b128 v[206:209], v53 offset:10432
	v_add_f32_dpp v0, v0, v0 row_ror:1 row_mask:0xf bank_mask:0xf bound_ctrl:1
	v_pk_fma_f32 v[84:85], v[0:1], v[18:19], v[108:109] op_sel_hi:[0,1,1]
	v_pk_fma_f32 v[86:87], v[0:1], v[20:21], v[110:111] op_sel_hi:[0,1,1]
	v_pk_mul_f32 v[250:251], v[84:85], v[122:123]
	v_pk_fma_f32 v[220:221], v[84:85], v[118:119], v[220:221]
	v_pk_fma_f32 v[250:251], v[86:87], v[124:125], v[250:251]
	v_pk_mul_f32 v[186:187], v[84:85], v[22:23]
	v_add_f32_e32 v0, v250, v251
	v_pk_fma_f32 v[222:223], v[86:87], v[120:121], v[222:223]
	v_pk_fma_f32 v[186:187], v[86:87], v[24:25], v[186:187]
	v_add_f32_dpp v0, v0, v0 row_ror:8 row_mask:0xf bank_mask:0xf bound_ctrl:1
	s_waitcnt lgkmcnt(7)
	v_pk_mul_f32 v[224:225], v[224:225], v[214:215] op_sel_hi:[1,0]
	v_add_f32_e32 v218, v186, v187
	v_add_f32_dpp v0, v0, v0 row_ror:4 row_mask:0xf bank_mask:0xf bound_ctrl:1
	v_pk_mul_f32 v[226:227], v[226:227], v[214:215] op_sel_hi:[1,0]
	ds_read_b128 v[108:111], v53 offset:11520
	ds_read_b32 v242, v65 offset:12032
	ds_read_b128 v[14:17], v53 offset:11008
	v_add_f32_dpp v0, v0, v0 row_ror:2 row_mask:0xf bank_mask:0xf bound_ctrl:1
	ds_read_b128 v[10:13], v53 offset:10752
	ds_read_b128 v[18:21], v53 offset:11264
	ds_read_b128 v[22:25], v53 offset:11776
	v_add_f32_dpp v0, v0, v0 row_ror:1 row_mask:0xf bank_mask:0xf bound_ctrl:1
	v_pk_fma_f32 v[84:85], v[0:1], v[134:135], v[220:221] op_sel_hi:[0,1,1]
	v_pk_fma_f32 v[86:87], v[0:1], v[136:137], v[222:223] op_sel_hi:[0,1,1]
	v_pk_mul_f32 v[250:251], v[84:85], v[142:143]
	v_pk_fma_f32 v[224:225], v[84:85], v[138:139], v[224:225]
	v_pk_fma_f32 v[250:251], v[86:87], v[144:145], v[250:251]
	v_pk_mul_f32 v[186:187], v[84:85], v[230:231]
	v_add_f32_e32 v0, v250, v251
	v_pk_fma_f32 v[226:227], v[86:87], v[140:141], v[226:227]
	v_pk_fma_f32 v[186:187], v[86:87], v[232:233], v[186:187]
	v_add_f32_dpp v0, v0, v0 row_ror:8 row_mask:0xf bank_mask:0xf bound_ctrl:1
	s_waitcnt lgkmcnt(6)
	v_pk_mul_f32 v[236:237], v[236:237], v[234:235] op_sel_hi:[1,0]
	v_add_f32_e32 v219, v186, v187
	v_add_f32_dpp v0, v0, v0 row_ror:4 row_mask:0xf bank_mask:0xf bound_ctrl:1
	v_pk_mul_f32 v[238:239], v[238:239], v[234:235] op_sel_hi:[1,0]
	ds_write2st64_b32 v77, v218, v219 offset0:16 offset1:20
	ds_read_b128 v[220:223], v53 offset:12864
	ds_read_b32 v246, v65 offset:13376
	ds_read_b128 v[122:125], v53 offset:12352
	v_add_f32_dpp v0, v0, v0 row_ror:2 row_mask:0xf bank_mask:0xf bound_ctrl:1
	ds_read_b128 v[118:121], v53 offset:12096
	ds_read_b128 v[134:137], v53 offset:12608
	ds_read_b128 v[230:233], v53 offset:13120
	v_add_f32_dpp v0, v0, v0 row_ror:1 row_mask:0xf bank_mask:0xf bound_ctrl:1
	v_pk_fma_f32 v[84:85], v[0:1], v[146:147], v[224:225] op_sel_hi:[0,1,1]
	v_pk_fma_f32 v[86:87], v[0:1], v[148:149], v[226:227] op_sel_hi:[0,1,1]
	v_pk_mul_f32 v[250:251], v[84:85], v[198:199]
	v_pk_fma_f32 v[236:237], v[84:85], v[194:195], v[236:237]
	v_pk_fma_f32 v[250:251], v[86:87], v[200:201], v[250:251]
	v_pk_mul_f32 v[186:187], v[84:85], v[150:151]
	v_add_f32_e32 v0, v250, v251
	v_pk_fma_f32 v[238:239], v[86:87], v[196:197], v[238:239]
	v_pk_fma_f32 v[186:187], v[86:87], v[152:153], v[186:187]
	v_add_f32_dpp v0, v0, v0 row_ror:8 row_mask:0xf bank_mask:0xf bound_ctrl:1
	s_waitcnt lgkmcnt(7)
	v_pk_mul_f32 v[108:109], v[108:109], v[242:243] op_sel_hi:[1,0]
	v_add_f32_e32 v218, v186, v187
	v_add_f32_dpp v0, v0, v0 row_ror:4 row_mask:0xf bank_mask:0xf bound_ctrl:1
	v_pk_mul_f32 v[110:111], v[110:111], v[242:243] op_sel_hi:[1,0]
	ds_read_b128 v[224:227], v53 offset:14208
	ds_read_b32 v214, v65 offset:14720
	ds_read_b128 v[142:145], v53 offset:13696
	v_add_f32_dpp v0, v0, v0 row_ror:2 row_mask:0xf bank_mask:0xf bound_ctrl:1
	ds_read_b128 v[138:141], v53 offset:13440
	ds_read_b128 v[146:149], v53 offset:13952
	ds_read_b128 v[150:153], v53 offset:14464
	v_add_f32_dpp v0, v0, v0 row_ror:1 row_mask:0xf bank_mask:0xf bound_ctrl:1
	v_pk_fma_f32 v[84:85], v[0:1], v[202:203], v[236:237] op_sel_hi:[0,1,1]
	v_pk_fma_f32 v[86:87], v[0:1], v[204:205], v[238:239] op_sel_hi:[0,1,1]
	v_pk_mul_f32 v[250:251], v[84:85], v[14:15]
	v_pk_fma_f32 v[108:109], v[84:85], v[10:11], v[108:109]
	v_pk_fma_f32 v[250:251], v[86:87], v[16:17], v[250:251]
	v_pk_mul_f32 v[186:187], v[84:85], v[206:207]
	v_add_f32_e32 v0, v250, v251
	v_pk_fma_f32 v[110:111], v[86:87], v[12:13], v[110:111]
	v_pk_fma_f32 v[186:187], v[86:87], v[208:209], v[186:187]
	v_add_f32_dpp v0, v0, v0 row_ror:8 row_mask:0xf bank_mask:0xf bound_ctrl:1
	s_waitcnt lgkmcnt(6)
	v_pk_mul_f32 v[220:221], v[220:221], v[246:247] op_sel_hi:[1,0]
	v_add_f32_e32 v219, v186, v187
	v_add_f32_dpp v0, v0, v0 row_ror:4 row_mask:0xf bank_mask:0xf bound_ctrl:1
	v_pk_mul_f32 v[222:223], v[222:223], v[246:247] op_sel_hi:[1,0]
	ds_write2st64_b32 v77, v218, v219 offset0:24 offset1:28
	ds_read_b128 v[236:239], v53 offset:15552
	ds_read_b32 v234, v65 offset:16064
	ds_read_b128 v[198:201], v53 offset:15040
	v_add_f32_dpp v0, v0, v0 row_ror:2 row_mask:0xf bank_mask:0xf bound_ctrl:1
	ds_read_b128 v[194:197], v53 offset:14784
	ds_read_b128 v[202:205], v53 offset:15296
	ds_read_b128 v[206:209], v53 offset:15808
	v_add_f32_dpp v0, v0, v0 row_ror:1 row_mask:0xf bank_mask:0xf bound_ctrl:1
	v_pk_fma_f32 v[84:85], v[0:1], v[18:19], v[108:109] op_sel_hi:[0,1,1]
	v_pk_fma_f32 v[86:87], v[0:1], v[20:21], v[110:111] op_sel_hi:[0,1,1]
	v_pk_mul_f32 v[250:251], v[84:85], v[122:123]
	v_pk_fma_f32 v[220:221], v[84:85], v[118:119], v[220:221]
	v_pk_fma_f32 v[250:251], v[86:87], v[124:125], v[250:251]
	v_pk_mul_f32 v[186:187], v[84:85], v[22:23]
	v_add_f32_e32 v0, v250, v251
	v_pk_fma_f32 v[222:223], v[86:87], v[120:121], v[222:223]
	v_pk_fma_f32 v[186:187], v[86:87], v[24:25], v[186:187]
	v_add_f32_dpp v0, v0, v0 row_ror:8 row_mask:0xf bank_mask:0xf bound_ctrl:1
	s_waitcnt lgkmcnt(7)
	v_pk_mul_f32 v[224:225], v[224:225], v[214:215] op_sel_hi:[1,0]
	v_add_f32_e32 v218, v186, v187
	v_add_f32_dpp v0, v0, v0 row_ror:4 row_mask:0xf bank_mask:0xf bound_ctrl:1
	v_pk_mul_f32 v[226:227], v[226:227], v[214:215] op_sel_hi:[1,0]
	ds_read_b128 v[108:111], v53 offset:16896
	ds_read_b32 v242, v65 offset:17408
	ds_read_b128 v[14:17], v53 offset:16384
	v_add_f32_dpp v0, v0, v0 row_ror:2 row_mask:0xf bank_mask:0xf bound_ctrl:1
	ds_read_b128 v[10:13], v53 offset:16128
	ds_read_b128 v[18:21], v53 offset:16640
	ds_read_b128 v[22:25], v53 offset:17152
	v_add_f32_dpp v0, v0, v0 row_ror:1 row_mask:0xf bank_mask:0xf bound_ctrl:1
	v_pk_fma_f32 v[84:85], v[0:1], v[134:135], v[220:221] op_sel_hi:[0,1,1]
	v_pk_fma_f32 v[86:87], v[0:1], v[136:137], v[222:223] op_sel_hi:[0,1,1]
	v_pk_mul_f32 v[250:251], v[84:85], v[142:143]
	v_pk_fma_f32 v[224:225], v[84:85], v[138:139], v[224:225]
	v_pk_fma_f32 v[250:251], v[86:87], v[144:145], v[250:251]
	v_pk_mul_f32 v[186:187], v[84:85], v[230:231]
	v_add_f32_e32 v0, v250, v251
	v_pk_fma_f32 v[226:227], v[86:87], v[140:141], v[226:227]
	v_pk_fma_f32 v[186:187], v[86:87], v[232:233], v[186:187]
	v_add_f32_dpp v0, v0, v0 row_ror:8 row_mask:0xf bank_mask:0xf bound_ctrl:1
	s_waitcnt lgkmcnt(6)
	v_pk_mul_f32 v[236:237], v[236:237], v[234:235] op_sel_hi:[1,0]
	v_add_f32_e32 v219, v186, v187
	v_add_f32_dpp v0, v0, v0 row_ror:4 row_mask:0xf bank_mask:0xf bound_ctrl:1
	v_pk_mul_f32 v[238:239], v[238:239], v[234:235] op_sel_hi:[1,0]
	ds_write2st64_b32 v77, v218, v219 offset0:32 offset1:36
	ds_read_b128 v[220:223], v53 offset:18240
	ds_read_b32 v246, v65 offset:18752
	ds_read_b128 v[122:125], v53 offset:17728
	v_add_f32_dpp v0, v0, v0 row_ror:2 row_mask:0xf bank_mask:0xf bound_ctrl:1
	ds_read_b128 v[118:121], v53 offset:17472
	ds_read_b128 v[134:137], v53 offset:17984
	ds_read_b128 v[230:233], v53 offset:18496
	v_add_f32_dpp v0, v0, v0 row_ror:1 row_mask:0xf bank_mask:0xf bound_ctrl:1
	v_pk_fma_f32 v[84:85], v[0:1], v[146:147], v[224:225] op_sel_hi:[0,1,1]
	v_pk_fma_f32 v[86:87], v[0:1], v[148:149], v[226:227] op_sel_hi:[0,1,1]
	v_pk_mul_f32 v[250:251], v[84:85], v[198:199]
	v_pk_fma_f32 v[236:237], v[84:85], v[194:195], v[236:237]
	v_pk_fma_f32 v[250:251], v[86:87], v[200:201], v[250:251]
	v_pk_mul_f32 v[186:187], v[84:85], v[150:151]
	v_add_f32_e32 v0, v250, v251
	v_pk_fma_f32 v[238:239], v[86:87], v[196:197], v[238:239]
	v_pk_fma_f32 v[186:187], v[86:87], v[152:153], v[186:187]
	v_add_f32_dpp v0, v0, v0 row_ror:8 row_mask:0xf bank_mask:0xf bound_ctrl:1
	s_waitcnt lgkmcnt(7)
	v_pk_mul_f32 v[108:109], v[108:109], v[242:243] op_sel_hi:[1,0]
	v_add_f32_e32 v218, v186, v187
	v_add_f32_dpp v0, v0, v0 row_ror:4 row_mask:0xf bank_mask:0xf bound_ctrl:1
	v_pk_mul_f32 v[110:111], v[110:111], v[242:243] op_sel_hi:[1,0]
	ds_read_b128 v[224:227], v53 offset:19584
	ds_read_b32 v214, v65 offset:20096
	ds_read_b128 v[142:145], v53 offset:19072
	v_add_f32_dpp v0, v0, v0 row_ror:2 row_mask:0xf bank_mask:0xf bound_ctrl:1
	ds_read_b128 v[138:141], v53 offset:18816
	ds_read_b128 v[146:149], v53 offset:19328
	ds_read_b128 v[150:153], v53 offset:19840
	v_add_f32_dpp v0, v0, v0 row_ror:1 row_mask:0xf bank_mask:0xf bound_ctrl:1
	v_pk_fma_f32 v[84:85], v[0:1], v[202:203], v[236:237] op_sel_hi:[0,1,1]
	v_pk_fma_f32 v[86:87], v[0:1], v[204:205], v[238:239] op_sel_hi:[0,1,1]
	v_pk_mul_f32 v[250:251], v[84:85], v[14:15]
	v_pk_fma_f32 v[108:109], v[84:85], v[10:11], v[108:109]
	v_pk_fma_f32 v[250:251], v[86:87], v[16:17], v[250:251]
	v_pk_mul_f32 v[186:187], v[84:85], v[206:207]
	v_add_f32_e32 v0, v250, v251
	v_pk_fma_f32 v[110:111], v[86:87], v[12:13], v[110:111]
	v_pk_fma_f32 v[186:187], v[86:87], v[208:209], v[186:187]
	v_add_f32_dpp v0, v0, v0 row_ror:8 row_mask:0xf bank_mask:0xf bound_ctrl:1
	s_waitcnt lgkmcnt(6)
	v_pk_mul_f32 v[220:221], v[220:221], v[246:247] op_sel_hi:[1,0]
	v_add_f32_e32 v219, v186, v187
	v_add_f32_dpp v0, v0, v0 row_ror:4 row_mask:0xf bank_mask:0xf bound_ctrl:1
	v_pk_mul_f32 v[222:223], v[222:223], v[246:247] op_sel_hi:[1,0]
	ds_write2st64_b32 v77, v218, v219 offset0:40 offset1:44
	ds_read_b128 v[236:239], v53 offset:20928
	ds_read_b32 v234, v65 offset:21440
	ds_read_b128 v[198:201], v53 offset:20416
	v_add_f32_dpp v0, v0, v0 row_ror:2 row_mask:0xf bank_mask:0xf bound_ctrl:1
	ds_read_b128 v[194:197], v53 offset:20160
	ds_read_b128 v[202:205], v53 offset:20672
	ds_read_b128 v[206:209], v53 offset:21184
	v_add_f32_dpp v0, v0, v0 row_ror:1 row_mask:0xf bank_mask:0xf bound_ctrl:1
	v_pk_fma_f32 v[84:85], v[0:1], v[18:19], v[108:109] op_sel_hi:[0,1,1]
	v_pk_fma_f32 v[86:87], v[0:1], v[20:21], v[110:111] op_sel_hi:[0,1,1]
	v_pk_mul_f32 v[250:251], v[84:85], v[122:123]
	v_pk_fma_f32 v[220:221], v[84:85], v[118:119], v[220:221]
	v_pk_fma_f32 v[250:251], v[86:87], v[124:125], v[250:251]
	v_pk_mul_f32 v[186:187], v[84:85], v[22:23]
	v_add_f32_e32 v0, v250, v251
	v_pk_fma_f32 v[222:223], v[86:87], v[120:121], v[222:223]
	v_pk_fma_f32 v[186:187], v[86:87], v[24:25], v[186:187]
	v_add_f32_dpp v0, v0, v0 row_ror:8 row_mask:0xf bank_mask:0xf bound_ctrl:1
	s_waitcnt lgkmcnt(7)
	v_pk_mul_f32 v[224:225], v[224:225], v[214:215] op_sel_hi:[1,0]
	v_add_f32_e32 v218, v186, v187
	v_add_f32_dpp v0, v0, v0 row_ror:4 row_mask:0xf bank_mask:0xf bound_ctrl:1
	v_pk_mul_f32 v[226:227], v[226:227], v[214:215] op_sel_hi:[1,0]
	ds_read_b128 v[108:111], v53 offset:22272
	ds_read_b32 v242, v65 offset:22784
	ds_read_b128 v[14:17], v53 offset:21760
	v_add_f32_dpp v0, v0, v0 row_ror:2 row_mask:0xf bank_mask:0xf bound_ctrl:1
	ds_read_b128 v[10:13], v53 offset:21504
	ds_read_b128 v[18:21], v53 offset:22016
	ds_read_b128 v[22:25], v53 offset:22528
	v_add_f32_dpp v0, v0, v0 row_ror:1 row_mask:0xf bank_mask:0xf bound_ctrl:1
	v_pk_fma_f32 v[84:85], v[0:1], v[134:135], v[220:221] op_sel_hi:[0,1,1]
	v_pk_fma_f32 v[86:87], v[0:1], v[136:137], v[222:223] op_sel_hi:[0,1,1]
	v_pk_mul_f32 v[250:251], v[84:85], v[142:143]
	v_pk_fma_f32 v[224:225], v[84:85], v[138:139], v[224:225]
	v_pk_fma_f32 v[250:251], v[86:87], v[144:145], v[250:251]
	v_pk_mul_f32 v[186:187], v[84:85], v[230:231]
	v_add_f32_e32 v0, v250, v251
	v_pk_fma_f32 v[226:227], v[86:87], v[140:141], v[226:227]
	v_pk_fma_f32 v[186:187], v[86:87], v[232:233], v[186:187]
	v_add_f32_dpp v0, v0, v0 row_ror:8 row_mask:0xf bank_mask:0xf bound_ctrl:1
	s_waitcnt lgkmcnt(6)
	v_pk_mul_f32 v[236:237], v[236:237], v[234:235] op_sel_hi:[1,0]
	v_add_f32_e32 v219, v186, v187
	v_add_f32_dpp v0, v0, v0 row_ror:4 row_mask:0xf bank_mask:0xf bound_ctrl:1
	v_pk_mul_f32 v[238:239], v[238:239], v[234:235] op_sel_hi:[1,0]
	ds_write2st64_b32 v77, v218, v219 offset0:48 offset1:52
	ds_read_b128 v[220:223], v53 offset:23616
	ds_read_b32 v246, v65 offset:24128
	ds_read_b128 v[122:125], v53 offset:23104
	v_add_f32_dpp v0, v0, v0 row_ror:2 row_mask:0xf bank_mask:0xf bound_ctrl:1
	ds_read_b128 v[118:121], v53 offset:22848
	ds_read_b128 v[134:137], v53 offset:23360
	ds_read_b128 v[230:233], v53 offset:23872
	v_add_f32_dpp v0, v0, v0 row_ror:1 row_mask:0xf bank_mask:0xf bound_ctrl:1
	v_pk_fma_f32 v[84:85], v[0:1], v[146:147], v[224:225] op_sel_hi:[0,1,1]
	v_pk_fma_f32 v[86:87], v[0:1], v[148:149], v[226:227] op_sel_hi:[0,1,1]
	v_pk_mul_f32 v[250:251], v[84:85], v[198:199]
	v_pk_fma_f32 v[236:237], v[84:85], v[194:195], v[236:237]
	v_pk_fma_f32 v[250:251], v[86:87], v[200:201], v[250:251]
	v_pk_mul_f32 v[186:187], v[84:85], v[150:151]
	v_add_f32_e32 v0, v250, v251
	v_pk_fma_f32 v[238:239], v[86:87], v[196:197], v[238:239]
	v_pk_fma_f32 v[186:187], v[86:87], v[152:153], v[186:187]
	v_add_f32_dpp v0, v0, v0 row_ror:8 row_mask:0xf bank_mask:0xf bound_ctrl:1
	s_waitcnt lgkmcnt(7)
	v_pk_mul_f32 v[108:109], v[108:109], v[242:243] op_sel_hi:[1,0]
	v_add_f32_e32 v218, v186, v187
	v_add_f32_dpp v0, v0, v0 row_ror:4 row_mask:0xf bank_mask:0xf bound_ctrl:1
	v_pk_mul_f32 v[110:111], v[110:111], v[242:243] op_sel_hi:[1,0]
	ds_read_b128 v[224:227], v53 offset:24960
	ds_read_b32 v214, v65 offset:25472
	ds_read_b128 v[142:145], v53 offset:24448
	v_add_f32_dpp v0, v0, v0 row_ror:2 row_mask:0xf bank_mask:0xf bound_ctrl:1
	ds_read_b128 v[138:141], v53 offset:24192
	ds_read_b128 v[146:149], v53 offset:24704
	ds_read_b128 v[150:153], v53 offset:25216
	v_add_f32_dpp v0, v0, v0 row_ror:1 row_mask:0xf bank_mask:0xf bound_ctrl:1
	v_pk_fma_f32 v[84:85], v[0:1], v[202:203], v[236:237] op_sel_hi:[0,1,1]
	v_pk_fma_f32 v[86:87], v[0:1], v[204:205], v[238:239] op_sel_hi:[0,1,1]
	v_pk_mul_f32 v[250:251], v[84:85], v[14:15]
	v_pk_fma_f32 v[108:109], v[84:85], v[10:11], v[108:109]
	v_pk_fma_f32 v[250:251], v[86:87], v[16:17], v[250:251]
	v_pk_mul_f32 v[186:187], v[84:85], v[206:207]
	v_add_f32_e32 v0, v250, v251
	v_pk_fma_f32 v[110:111], v[86:87], v[12:13], v[110:111]
	v_pk_fma_f32 v[186:187], v[86:87], v[208:209], v[186:187]
	v_add_f32_dpp v0, v0, v0 row_ror:8 row_mask:0xf bank_mask:0xf bound_ctrl:1
	s_waitcnt lgkmcnt(6)
	v_pk_mul_f32 v[220:221], v[220:221], v[246:247] op_sel_hi:[1,0]
	v_add_f32_e32 v219, v186, v187
	v_add_f32_dpp v0, v0, v0 row_ror:4 row_mask:0xf bank_mask:0xf bound_ctrl:1
	v_pk_mul_f32 v[222:223], v[222:223], v[246:247] op_sel_hi:[1,0]
	ds_write2st64_b32 v77, v218, v219 offset0:56 offset1:60
	ds_read_b128 v[236:239], v53 offset:26304
	ds_read_b32 v234, v65 offset:26816
	ds_read_b128 v[198:201], v53 offset:25792
	v_add_f32_dpp v0, v0, v0 row_ror:2 row_mask:0xf bank_mask:0xf bound_ctrl:1
	ds_read_b128 v[194:197], v53 offset:25536
	ds_read_b128 v[202:205], v53 offset:26048
	ds_read_b128 v[206:209], v53 offset:26560
	v_add_f32_dpp v0, v0, v0 row_ror:1 row_mask:0xf bank_mask:0xf bound_ctrl:1
	v_pk_fma_f32 v[84:85], v[0:1], v[18:19], v[108:109] op_sel_hi:[0,1,1]
	v_pk_fma_f32 v[86:87], v[0:1], v[20:21], v[110:111] op_sel_hi:[0,1,1]
	v_pk_mul_f32 v[250:251], v[84:85], v[122:123]
	v_pk_fma_f32 v[220:221], v[84:85], v[118:119], v[220:221]
	v_pk_fma_f32 v[250:251], v[86:87], v[124:125], v[250:251]
	v_pk_mul_f32 v[186:187], v[84:85], v[22:23]
	v_add_f32_e32 v0, v250, v251
	v_pk_fma_f32 v[222:223], v[86:87], v[120:121], v[222:223]
	v_pk_fma_f32 v[186:187], v[86:87], v[24:25], v[186:187]
	v_add_f32_dpp v0, v0, v0 row_ror:8 row_mask:0xf bank_mask:0xf bound_ctrl:1
	s_waitcnt lgkmcnt(7)
	v_pk_mul_f32 v[224:225], v[224:225], v[214:215] op_sel_hi:[1,0]
	v_add_f32_e32 v218, v186, v187
	v_add_f32_dpp v0, v0, v0 row_ror:4 row_mask:0xf bank_mask:0xf bound_ctrl:1
	v_pk_mul_f32 v[226:227], v[226:227], v[214:215] op_sel_hi:[1,0]
	ds_read_b128 v[108:111], v53 offset:27648
	ds_read_b32 v242, v65 offset:28160
	ds_read_b128 v[14:17], v53 offset:27136
	v_add_f32_dpp v0, v0, v0 row_ror:2 row_mask:0xf bank_mask:0xf bound_ctrl:1
	ds_read_b128 v[10:13], v53 offset:26880
	ds_read_b128 v[18:21], v53 offset:27392
	ds_read_b128 v[22:25], v53 offset:27904
	v_add_f32_dpp v0, v0, v0 row_ror:1 row_mask:0xf bank_mask:0xf bound_ctrl:1
	v_pk_fma_f32 v[84:85], v[0:1], v[134:135], v[220:221] op_sel_hi:[0,1,1]
	v_pk_fma_f32 v[86:87], v[0:1], v[136:137], v[222:223] op_sel_hi:[0,1,1]
	v_pk_mul_f32 v[250:251], v[84:85], v[142:143]
	v_pk_fma_f32 v[224:225], v[84:85], v[138:139], v[224:225]
	v_pk_fma_f32 v[250:251], v[86:87], v[144:145], v[250:251]
	v_pk_mul_f32 v[186:187], v[84:85], v[230:231]
	v_add_f32_e32 v0, v250, v251
	v_pk_fma_f32 v[226:227], v[86:87], v[140:141], v[226:227]
	v_pk_fma_f32 v[186:187], v[86:87], v[232:233], v[186:187]
	v_add_f32_dpp v0, v0, v0 row_ror:8 row_mask:0xf bank_mask:0xf bound_ctrl:1
	s_waitcnt lgkmcnt(6)
	v_pk_mul_f32 v[236:237], v[236:237], v[234:235] op_sel_hi:[1,0]
	v_add_f32_e32 v219, v186, v187
	v_add_f32_dpp v0, v0, v0 row_ror:4 row_mask:0xf bank_mask:0xf bound_ctrl:1
	v_pk_mul_f32 v[238:239], v[238:239], v[234:235] op_sel_hi:[1,0]
	ds_write2st64_b32 v77, v218, v219 offset0:64 offset1:68
	ds_read_b128 v[220:223], v53 offset:28992
	ds_read_b32 v246, v65 offset:29504
	ds_read_b128 v[122:125], v53 offset:28480
	v_add_f32_dpp v0, v0, v0 row_ror:2 row_mask:0xf bank_mask:0xf bound_ctrl:1
	ds_read_b128 v[118:121], v53 offset:28224
	ds_read_b128 v[134:137], v53 offset:28736
	ds_read_b128 v[230:233], v53 offset:29248
	v_add_f32_dpp v0, v0, v0 row_ror:1 row_mask:0xf bank_mask:0xf bound_ctrl:1
	v_pk_fma_f32 v[84:85], v[0:1], v[146:147], v[224:225] op_sel_hi:[0,1,1]
	v_pk_fma_f32 v[86:87], v[0:1], v[148:149], v[226:227] op_sel_hi:[0,1,1]
	v_pk_mul_f32 v[250:251], v[84:85], v[198:199]
	v_pk_fma_f32 v[236:237], v[84:85], v[194:195], v[236:237]
	v_pk_fma_f32 v[250:251], v[86:87], v[200:201], v[250:251]
	v_pk_mul_f32 v[186:187], v[84:85], v[150:151]
	v_add_f32_e32 v0, v250, v251
	v_pk_fma_f32 v[238:239], v[86:87], v[196:197], v[238:239]
	v_pk_fma_f32 v[186:187], v[86:87], v[152:153], v[186:187]
	v_add_f32_dpp v0, v0, v0 row_ror:8 row_mask:0xf bank_mask:0xf bound_ctrl:1
	s_waitcnt lgkmcnt(7)
	v_pk_mul_f32 v[108:109], v[108:109], v[242:243] op_sel_hi:[1,0]
	v_add_f32_e32 v218, v186, v187
	v_add_f32_dpp v0, v0, v0 row_ror:4 row_mask:0xf bank_mask:0xf bound_ctrl:1
	v_pk_mul_f32 v[110:111], v[110:111], v[242:243] op_sel_hi:[1,0]
	ds_read_b128 v[224:227], v53 offset:30336
	ds_read_b32 v214, v65 offset:30848
	ds_read_b128 v[142:145], v53 offset:29824
	v_add_f32_dpp v0, v0, v0 row_ror:2 row_mask:0xf bank_mask:0xf bound_ctrl:1
	ds_read_b128 v[138:141], v53 offset:29568
	ds_read_b128 v[146:149], v53 offset:30080
	ds_read_b128 v[150:153], v53 offset:30592
	v_add_f32_dpp v0, v0, v0 row_ror:1 row_mask:0xf bank_mask:0xf bound_ctrl:1
	v_pk_fma_f32 v[84:85], v[0:1], v[202:203], v[236:237] op_sel_hi:[0,1,1]
	v_pk_fma_f32 v[86:87], v[0:1], v[204:205], v[238:239] op_sel_hi:[0,1,1]
	v_pk_mul_f32 v[250:251], v[84:85], v[14:15]
	v_pk_fma_f32 v[108:109], v[84:85], v[10:11], v[108:109]
	v_pk_fma_f32 v[250:251], v[86:87], v[16:17], v[250:251]
	v_pk_mul_f32 v[186:187], v[84:85], v[206:207]
	v_add_f32_e32 v0, v250, v251
	v_pk_fma_f32 v[110:111], v[86:87], v[12:13], v[110:111]
	v_pk_fma_f32 v[186:187], v[86:87], v[208:209], v[186:187]
	v_add_f32_dpp v0, v0, v0 row_ror:8 row_mask:0xf bank_mask:0xf bound_ctrl:1
	s_waitcnt lgkmcnt(6)
	v_pk_mul_f32 v[220:221], v[220:221], v[246:247] op_sel_hi:[1,0]
	v_add_f32_e32 v219, v186, v187
	v_add_f32_dpp v0, v0, v0 row_ror:4 row_mask:0xf bank_mask:0xf bound_ctrl:1
	v_pk_mul_f32 v[222:223], v[222:223], v[246:247] op_sel_hi:[1,0]
	ds_write2st64_b32 v77, v218, v219 offset0:72 offset1:76
	ds_read_b128 v[236:239], v53 offset:31680
	ds_read_b32 v234, v65 offset:32192
	ds_read_b128 v[198:201], v53 offset:31168
	v_add_f32_dpp v0, v0, v0 row_ror:2 row_mask:0xf bank_mask:0xf bound_ctrl:1
	ds_read_b128 v[194:197], v53 offset:30912
	ds_read_b128 v[202:205], v53 offset:31424
	ds_read_b128 v[206:209], v53 offset:31936
	v_add_f32_dpp v0, v0, v0 row_ror:1 row_mask:0xf bank_mask:0xf bound_ctrl:1
	v_pk_fma_f32 v[84:85], v[0:1], v[18:19], v[108:109] op_sel_hi:[0,1,1]
	v_pk_fma_f32 v[86:87], v[0:1], v[20:21], v[110:111] op_sel_hi:[0,1,1]
	v_pk_mul_f32 v[250:251], v[84:85], v[122:123]
	v_pk_fma_f32 v[220:221], v[84:85], v[118:119], v[220:221]
	v_pk_fma_f32 v[250:251], v[86:87], v[124:125], v[250:251]
	v_pk_mul_f32 v[186:187], v[84:85], v[22:23]
	v_add_f32_e32 v0, v250, v251
	v_pk_fma_f32 v[222:223], v[86:87], v[120:121], v[222:223]
	v_pk_fma_f32 v[186:187], v[86:87], v[24:25], v[186:187]
	v_add_f32_dpp v0, v0, v0 row_ror:8 row_mask:0xf bank_mask:0xf bound_ctrl:1
	s_waitcnt lgkmcnt(7)
	v_pk_mul_f32 v[224:225], v[224:225], v[214:215] op_sel_hi:[1,0]
	v_add_f32_e32 v218, v186, v187
	v_add_f32_dpp v0, v0, v0 row_ror:4 row_mask:0xf bank_mask:0xf bound_ctrl:1
	v_pk_mul_f32 v[226:227], v[226:227], v[214:215] op_sel_hi:[1,0]
	ds_read_b128 v[108:111], v53 offset:33024
	ds_read_b32 v242, v65 offset:33536
	ds_read_b128 v[14:17], v53 offset:32512
	v_add_f32_dpp v0, v0, v0 row_ror:2 row_mask:0xf bank_mask:0xf bound_ctrl:1
	ds_read_b128 v[10:13], v53 offset:32256
	ds_read_b128 v[18:21], v53 offset:32768
	ds_read_b128 v[22:25], v53 offset:33280
	v_add_f32_dpp v0, v0, v0 row_ror:1 row_mask:0xf bank_mask:0xf bound_ctrl:1
	v_pk_fma_f32 v[84:85], v[0:1], v[134:135], v[220:221] op_sel_hi:[0,1,1]
	v_pk_fma_f32 v[86:87], v[0:1], v[136:137], v[222:223] op_sel_hi:[0,1,1]
	v_pk_mul_f32 v[250:251], v[84:85], v[142:143]
	v_pk_fma_f32 v[224:225], v[84:85], v[138:139], v[224:225]
	v_pk_fma_f32 v[250:251], v[86:87], v[144:145], v[250:251]
	v_pk_mul_f32 v[186:187], v[84:85], v[230:231]
	v_add_f32_e32 v0, v250, v251
	v_pk_fma_f32 v[226:227], v[86:87], v[140:141], v[226:227]
	v_pk_fma_f32 v[186:187], v[86:87], v[232:233], v[186:187]
	v_add_f32_dpp v0, v0, v0 row_ror:8 row_mask:0xf bank_mask:0xf bound_ctrl:1
	s_waitcnt lgkmcnt(6)
	v_pk_mul_f32 v[236:237], v[236:237], v[234:235] op_sel_hi:[1,0]
	v_add_f32_e32 v219, v186, v187
	v_add_f32_dpp v0, v0, v0 row_ror:4 row_mask:0xf bank_mask:0xf bound_ctrl:1
	v_pk_mul_f32 v[238:239], v[238:239], v[234:235] op_sel_hi:[1,0]
	ds_write2st64_b32 v77, v218, v219 offset0:80 offset1:84
	ds_read_b128 v[220:223], v53 offset:34368
	ds_read_b32 v246, v65 offset:34880
	ds_read_b128 v[122:125], v53 offset:33856
	v_add_f32_dpp v0, v0, v0 row_ror:2 row_mask:0xf bank_mask:0xf bound_ctrl:1
	ds_read_b128 v[118:121], v53 offset:33600
	ds_read_b128 v[134:137], v53 offset:34112
	ds_read_b128 v[230:233], v53 offset:34624
	v_add_f32_dpp v0, v0, v0 row_ror:1 row_mask:0xf bank_mask:0xf bound_ctrl:1
	v_pk_fma_f32 v[84:85], v[0:1], v[146:147], v[224:225] op_sel_hi:[0,1,1]
	v_pk_fma_f32 v[86:87], v[0:1], v[148:149], v[226:227] op_sel_hi:[0,1,1]
	v_pk_mul_f32 v[250:251], v[84:85], v[198:199]
	v_pk_fma_f32 v[236:237], v[84:85], v[194:195], v[236:237]
	v_pk_fma_f32 v[250:251], v[86:87], v[200:201], v[250:251]
	v_pk_mul_f32 v[186:187], v[84:85], v[150:151]
	v_add_f32_e32 v0, v250, v251
	v_pk_fma_f32 v[238:239], v[86:87], v[196:197], v[238:239]
	v_pk_fma_f32 v[186:187], v[86:87], v[152:153], v[186:187]
	v_add_f32_dpp v0, v0, v0 row_ror:8 row_mask:0xf bank_mask:0xf bound_ctrl:1
	s_waitcnt lgkmcnt(7)
	v_pk_mul_f32 v[108:109], v[108:109], v[242:243] op_sel_hi:[1,0]
	v_add_f32_e32 v218, v186, v187
	v_add_f32_dpp v0, v0, v0 row_ror:4 row_mask:0xf bank_mask:0xf bound_ctrl:1
	v_pk_mul_f32 v[110:111], v[110:111], v[242:243] op_sel_hi:[1,0]
	ds_read_b128 v[224:227], v53 offset:35712
	ds_read_b32 v214, v65 offset:36224
	ds_read_b128 v[142:145], v53 offset:35200
	v_add_f32_dpp v0, v0, v0 row_ror:2 row_mask:0xf bank_mask:0xf bound_ctrl:1
	ds_read_b128 v[138:141], v53 offset:34944
	ds_read_b128 v[146:149], v53 offset:35456
	ds_read_b128 v[150:153], v53 offset:35968
	v_add_f32_dpp v0, v0, v0 row_ror:1 row_mask:0xf bank_mask:0xf bound_ctrl:1
	v_pk_fma_f32 v[84:85], v[0:1], v[202:203], v[236:237] op_sel_hi:[0,1,1]
	v_pk_fma_f32 v[86:87], v[0:1], v[204:205], v[238:239] op_sel_hi:[0,1,1]
	v_pk_mul_f32 v[250:251], v[84:85], v[14:15]
	v_pk_fma_f32 v[108:109], v[84:85], v[10:11], v[108:109]
	v_pk_fma_f32 v[250:251], v[86:87], v[16:17], v[250:251]
	v_pk_mul_f32 v[186:187], v[84:85], v[206:207]
	v_add_f32_e32 v0, v250, v251
	v_pk_fma_f32 v[110:111], v[86:87], v[12:13], v[110:111]
	v_pk_fma_f32 v[186:187], v[86:87], v[208:209], v[186:187]
	v_add_f32_dpp v0, v0, v0 row_ror:8 row_mask:0xf bank_mask:0xf bound_ctrl:1
	s_waitcnt lgkmcnt(6)
	v_pk_mul_f32 v[220:221], v[220:221], v[246:247] op_sel_hi:[1,0]
	v_add_f32_e32 v219, v186, v187
	v_add_f32_dpp v0, v0, v0 row_ror:4 row_mask:0xf bank_mask:0xf bound_ctrl:1
	v_pk_mul_f32 v[222:223], v[222:223], v[246:247] op_sel_hi:[1,0]
	ds_write2st64_b32 v77, v218, v219 offset0:88 offset1:92
	ds_read_b128 v[236:239], v53 offset:37056
	ds_read_b32 v234, v65 offset:37568
	ds_read_b128 v[198:201], v53 offset:36544
	v_add_f32_dpp v0, v0, v0 row_ror:2 row_mask:0xf bank_mask:0xf bound_ctrl:1
	ds_read_b128 v[194:197], v53 offset:36288
	ds_read_b128 v[202:205], v53 offset:36800
	ds_read_b128 v[206:209], v53 offset:37312
	v_add_f32_dpp v0, v0, v0 row_ror:1 row_mask:0xf bank_mask:0xf bound_ctrl:1
	v_pk_fma_f32 v[84:85], v[0:1], v[18:19], v[108:109] op_sel_hi:[0,1,1]
	v_pk_fma_f32 v[86:87], v[0:1], v[20:21], v[110:111] op_sel_hi:[0,1,1]
	v_pk_mul_f32 v[250:251], v[84:85], v[122:123]
	v_pk_fma_f32 v[220:221], v[84:85], v[118:119], v[220:221]
	v_pk_fma_f32 v[250:251], v[86:87], v[124:125], v[250:251]
	v_pk_mul_f32 v[186:187], v[84:85], v[22:23]
	v_add_f32_e32 v0, v250, v251
	v_pk_fma_f32 v[222:223], v[86:87], v[120:121], v[222:223]
	v_pk_fma_f32 v[186:187], v[86:87], v[24:25], v[186:187]
	v_add_f32_dpp v0, v0, v0 row_ror:8 row_mask:0xf bank_mask:0xf bound_ctrl:1
	s_waitcnt lgkmcnt(7)
	v_pk_mul_f32 v[224:225], v[224:225], v[214:215] op_sel_hi:[1,0]
	v_add_f32_e32 v218, v186, v187
	v_add_f32_dpp v0, v0, v0 row_ror:4 row_mask:0xf bank_mask:0xf bound_ctrl:1
	v_pk_mul_f32 v[226:227], v[226:227], v[214:215] op_sel_hi:[1,0]
	ds_read_b128 v[108:111], v53 offset:38400
	ds_read_b32 v242, v65 offset:38912
	ds_read_b128 v[14:17], v53 offset:37888
	v_add_f32_dpp v0, v0, v0 row_ror:2 row_mask:0xf bank_mask:0xf bound_ctrl:1
	ds_read_b128 v[10:13], v53 offset:37632
	ds_read_b128 v[18:21], v53 offset:38144
	ds_read_b128 v[22:25], v53 offset:38656
	v_add_f32_dpp v0, v0, v0 row_ror:1 row_mask:0xf bank_mask:0xf bound_ctrl:1
	v_pk_fma_f32 v[84:85], v[0:1], v[134:135], v[220:221] op_sel_hi:[0,1,1]
	v_pk_fma_f32 v[86:87], v[0:1], v[136:137], v[222:223] op_sel_hi:[0,1,1]
	v_pk_mul_f32 v[250:251], v[84:85], v[142:143]
	v_pk_fma_f32 v[224:225], v[84:85], v[138:139], v[224:225]
	v_pk_fma_f32 v[250:251], v[86:87], v[144:145], v[250:251]
	v_pk_mul_f32 v[186:187], v[84:85], v[230:231]
	v_add_f32_e32 v0, v250, v251
	v_pk_fma_f32 v[226:227], v[86:87], v[140:141], v[226:227]
	v_pk_fma_f32 v[186:187], v[86:87], v[232:233], v[186:187]
	v_add_f32_dpp v0, v0, v0 row_ror:8 row_mask:0xf bank_mask:0xf bound_ctrl:1
	s_waitcnt lgkmcnt(6)
	v_pk_mul_f32 v[236:237], v[236:237], v[234:235] op_sel_hi:[1,0]
	v_add_f32_e32 v219, v186, v187
	v_add_f32_dpp v0, v0, v0 row_ror:4 row_mask:0xf bank_mask:0xf bound_ctrl:1
	v_pk_mul_f32 v[238:239], v[238:239], v[234:235] op_sel_hi:[1,0]
	ds_write2st64_b32 v77, v218, v219 offset0:96 offset1:100
	ds_read_b128 v[220:223], v53 offset:39744
	ds_read_b32 v246, v65 offset:40256
	ds_read_b128 v[122:125], v53 offset:39232
	v_add_f32_dpp v0, v0, v0 row_ror:2 row_mask:0xf bank_mask:0xf bound_ctrl:1
	ds_read_b128 v[118:121], v53 offset:38976
	ds_read_b128 v[134:137], v53 offset:39488
	ds_read_b128 v[230:233], v53 offset:40000
	v_add_f32_dpp v0, v0, v0 row_ror:1 row_mask:0xf bank_mask:0xf bound_ctrl:1
	v_pk_fma_f32 v[84:85], v[0:1], v[146:147], v[224:225] op_sel_hi:[0,1,1]
	v_pk_fma_f32 v[86:87], v[0:1], v[148:149], v[226:227] op_sel_hi:[0,1,1]
	v_pk_mul_f32 v[250:251], v[84:85], v[198:199]
	v_pk_fma_f32 v[236:237], v[84:85], v[194:195], v[236:237]
	v_pk_fma_f32 v[250:251], v[86:87], v[200:201], v[250:251]
	v_pk_mul_f32 v[186:187], v[84:85], v[150:151]
	v_add_f32_e32 v0, v250, v251
	v_pk_fma_f32 v[238:239], v[86:87], v[196:197], v[238:239]
	v_pk_fma_f32 v[186:187], v[86:87], v[152:153], v[186:187]
	v_add_f32_dpp v0, v0, v0 row_ror:8 row_mask:0xf bank_mask:0xf bound_ctrl:1
	s_waitcnt lgkmcnt(7)
	v_pk_mul_f32 v[108:109], v[108:109], v[242:243] op_sel_hi:[1,0]
	v_add_f32_e32 v218, v186, v187
	v_add_f32_dpp v0, v0, v0 row_ror:4 row_mask:0xf bank_mask:0xf bound_ctrl:1
	v_pk_mul_f32 v[110:111], v[110:111], v[242:243] op_sel_hi:[1,0]
	ds_read_b128 v[224:227], v53 offset:41088
	ds_read_b32 v214, v65 offset:41600
	ds_read_b128 v[142:145], v53 offset:40576
	v_add_f32_dpp v0, v0, v0 row_ror:2 row_mask:0xf bank_mask:0xf bound_ctrl:1
	ds_read_b128 v[138:141], v53 offset:40320
	ds_read_b128 v[146:149], v53 offset:40832
	ds_read_b128 v[150:153], v53 offset:41344
	v_add_f32_dpp v0, v0, v0 row_ror:1 row_mask:0xf bank_mask:0xf bound_ctrl:1
	v_pk_fma_f32 v[84:85], v[0:1], v[202:203], v[236:237] op_sel_hi:[0,1,1]
	v_pk_fma_f32 v[86:87], v[0:1], v[204:205], v[238:239] op_sel_hi:[0,1,1]
	v_pk_mul_f32 v[250:251], v[84:85], v[14:15]
	v_pk_fma_f32 v[108:109], v[84:85], v[10:11], v[108:109]
	v_pk_fma_f32 v[250:251], v[86:87], v[16:17], v[250:251]
	v_pk_mul_f32 v[186:187], v[84:85], v[206:207]
	v_add_f32_e32 v0, v250, v251
	v_pk_fma_f32 v[110:111], v[86:87], v[12:13], v[110:111]
	v_pk_fma_f32 v[186:187], v[86:87], v[208:209], v[186:187]
	v_add_f32_dpp v0, v0, v0 row_ror:8 row_mask:0xf bank_mask:0xf bound_ctrl:1
	s_waitcnt lgkmcnt(6)
	v_pk_mul_f32 v[220:221], v[220:221], v[246:247] op_sel_hi:[1,0]
	v_add_f32_e32 v219, v186, v187
	v_add_f32_dpp v0, v0, v0 row_ror:4 row_mask:0xf bank_mask:0xf bound_ctrl:1
	v_pk_mul_f32 v[222:223], v[222:223], v[246:247] op_sel_hi:[1,0]
	ds_write2st64_b32 v77, v218, v219 offset0:104 offset1:108
	ds_read_b128 v[236:239], v53 offset:42432
	ds_read_b32 v234, v65 offset:42944
	ds_read_b128 v[198:201], v53 offset:41920
	v_add_f32_dpp v0, v0, v0 row_ror:2 row_mask:0xf bank_mask:0xf bound_ctrl:1
	ds_read_b128 v[194:197], v53 offset:41664
	ds_read_b128 v[202:205], v53 offset:42176
	ds_read_b128 v[206:209], v53 offset:42688
	v_add_f32_dpp v0, v0, v0 row_ror:1 row_mask:0xf bank_mask:0xf bound_ctrl:1
	v_pk_fma_f32 v[84:85], v[0:1], v[18:19], v[108:109] op_sel_hi:[0,1,1]
	v_pk_fma_f32 v[86:87], v[0:1], v[20:21], v[110:111] op_sel_hi:[0,1,1]
	v_pk_mul_f32 v[250:251], v[84:85], v[122:123]
	v_pk_fma_f32 v[220:221], v[84:85], v[118:119], v[220:221]
	v_pk_fma_f32 v[250:251], v[86:87], v[124:125], v[250:251]
	v_pk_mul_f32 v[186:187], v[84:85], v[22:23]
	v_add_f32_e32 v0, v250, v251
	v_pk_fma_f32 v[222:223], v[86:87], v[120:121], v[222:223]
	v_pk_fma_f32 v[186:187], v[86:87], v[24:25], v[186:187]
	v_add_f32_dpp v0, v0, v0 row_ror:8 row_mask:0xf bank_mask:0xf bound_ctrl:1
	s_waitcnt lgkmcnt(7)
	v_pk_mul_f32 v[224:225], v[224:225], v[214:215] op_sel_hi:[1,0]
	v_add_f32_e32 v218, v186, v187
	v_add_f32_dpp v0, v0, v0 row_ror:4 row_mask:0xf bank_mask:0xf bound_ctrl:1
	v_pk_mul_f32 v[226:227], v[226:227], v[214:215] op_sel_hi:[1,0]
	s_nop 0
	v_add_f32_dpp v0, v0, v0 row_ror:2 row_mask:0xf bank_mask:0xf bound_ctrl:1
	s_nop 1
	v_add_f32_dpp v0, v0, v0 row_ror:1 row_mask:0xf bank_mask:0xf bound_ctrl:1
	v_pk_fma_f32 v[84:85], v[0:1], v[134:135], v[220:221] op_sel_hi:[0,1,1]
	v_pk_fma_f32 v[86:87], v[0:1], v[136:137], v[222:223] op_sel_hi:[0,1,1]
	v_pk_mul_f32 v[250:251], v[84:85], v[142:143]
	v_pk_fma_f32 v[224:225], v[84:85], v[138:139], v[224:225]
	v_pk_fma_f32 v[250:251], v[86:87], v[144:145], v[250:251]
	v_pk_mul_f32 v[186:187], v[84:85], v[230:231]
	v_add_f32_e32 v0, v250, v251
	v_pk_fma_f32 v[226:227], v[86:87], v[140:141], v[226:227]
	v_pk_fma_f32 v[186:187], v[86:87], v[232:233], v[186:187]
	v_add_f32_dpp v0, v0, v0 row_ror:8 row_mask:0xf bank_mask:0xf bound_ctrl:1
	s_waitcnt lgkmcnt(0)
	v_pk_mul_f32 v[236:237], v[236:237], v[234:235] op_sel_hi:[1,0]
	v_add_f32_e32 v219, v186, v187
	v_add_f32_dpp v0, v0, v0 row_ror:4 row_mask:0xf bank_mask:0xf bound_ctrl:1
	v_pk_mul_f32 v[238:239], v[238:239], v[234:235] op_sel_hi:[1,0]
	ds_write2st64_b32 v77, v218, v219 offset0:112 offset1:116
	v_add_f32_dpp v0, v0, v0 row_ror:2 row_mask:0xf bank_mask:0xf bound_ctrl:1
	s_nop 1
	v_add_f32_dpp v0, v0, v0 row_ror:1 row_mask:0xf bank_mask:0xf bound_ctrl:1
	v_pk_fma_f32 v[84:85], v[0:1], v[146:147], v[224:225] op_sel_hi:[0,1,1]
	v_pk_fma_f32 v[86:87], v[0:1], v[148:149], v[226:227] op_sel_hi:[0,1,1]
	v_pk_mul_f32 v[250:251], v[84:85], v[198:199]
	v_pk_fma_f32 v[236:237], v[84:85], v[194:195], v[236:237]
	v_pk_fma_f32 v[250:251], v[86:87], v[200:201], v[250:251]
	v_pk_mul_f32 v[186:187], v[84:85], v[150:151]
	v_add_f32_e32 v0, v250, v251
	v_pk_fma_f32 v[238:239], v[86:87], v[196:197], v[238:239]
	v_pk_fma_f32 v[186:187], v[86:87], v[152:153], v[186:187]
	v_add_f32_dpp v0, v0, v0 row_ror:8 row_mask:0xf bank_mask:0xf bound_ctrl:1
	v_add_f32_e32 v218, v186, v187
	s_nop 0
	v_add_f32_dpp v0, v0, v0 row_ror:4 row_mask:0xf bank_mask:0xf bound_ctrl:1
	s_nop 1
	v_add_f32_dpp v0, v0, v0 row_ror:2 row_mask:0xf bank_mask:0xf bound_ctrl:1
	s_nop 1
	v_add_f32_dpp v0, v0, v0 row_ror:1 row_mask:0xf bank_mask:0xf bound_ctrl:1
	v_pk_fma_f32 v[84:85], v[0:1], v[202:203], v[236:237] op_sel_hi:[0,1,1]
	v_pk_fma_f32 v[86:87], v[0:1], v[204:205], v[238:239] op_sel_hi:[0,1,1]
	v_pk_mul_f32 v[186:187], v[84:85], v[206:207]
	s_nop 0
	v_pk_fma_f32 v[186:187], v[86:87], v[208:209], v[186:187]
	s_nop 0
	v_add_f32_e32 v219, v186, v187
	ds_write2st64_b32 v77, v218, v219 offset0:120 offset1:124

.LBB0_647:
	s_or_b64 exec, exec, s[34:35]
	s_waitcnt lgkmcnt(0)
	s_barrier
	s_and_saveexec_b64 s[34:35], s[2:3]
	s_xor_b64 s[50:51], exec, s[34:35]
	s_cbranch_execz .LBB0_650
	s_and_b64 vcc, exec, s[8:9]
	s_cbranch_vccnz .LBB0_650
	ds_read_b128 v[108:111], v96 offset:768
	ds_read_b32 v242, v97
	ds_read_b128 v[14:17], v96 offset:256
	ds_read_b128 v[10:13], v96
	ds_read_b128 v[18:21], v96 offset:512
	ds_read_b128 v[22:25], v96 offset:1024
	ds_read_b128 v[220:223], v96 offset:2112
	ds_read_b32 v246, v97 offset:1344
	ds_read_b128 v[122:125], v96 offset:1600
	ds_read_b128 v[118:121], v96 offset:1344
	ds_read_b128 v[134:137], v96 offset:1856
	ds_read_b128 v[230:233], v96 offset:2368
	ds_read_b128 v[224:227], v96 offset:3456
	ds_read_b32 v214, v97 offset:2688
	ds_read_b128 v[142:145], v96 offset:2944
	ds_read_b128 v[138:141], v96 offset:2688
	ds_read_b128 v[146:149], v96 offset:3200
	ds_read_b128 v[150:153], v96 offset:3712
	s_waitcnt lgkmcnt(15)
	v_pk_mul_f32 v[108:109], v[108:109], v[242:243] op_sel_hi:[1,0]
	v_pk_mul_f32 v[110:111], v[110:111], v[242:243] op_sel_hi:[1,0]
	v_pk_mul_f32 v[250:251], v[84:85], v[14:15]
	s_waitcnt lgkmcnt(14)
	v_pk_fma_f32 v[108:109], v[84:85], v[10:11], v[108:109]
	v_pk_fma_f32 v[250:251], v[86:87], v[16:17], v[250:251]
	s_nop 0
	v_add_f32_e32 v0, v250, v251
	v_pk_fma_f32 v[110:111], v[86:87], v[12:13], v[110:111]
	s_nop 0
	v_add_f32_dpp v0, v0, v0 row_ror:8 row_mask:0xf bank_mask:0xf bound_ctrl:1
	s_waitcnt lgkmcnt(6)
	v_pk_mul_f32 v[220:221], v[220:221], v[246:247] op_sel_hi:[1,0]
	v_add_f32_dpp v0, v0, v0 row_ror:4 row_mask:0xf bank_mask:0xf bound_ctrl:1
	v_pk_mul_f32 v[222:223], v[222:223], v[246:247] op_sel_hi:[1,0]
	ds_read_b128 v[236:239], v96 offset:4800
	ds_read_b32 v234, v97 offset:4032
	ds_read_b128 v[198:201], v96 offset:4288
	v_add_f32_dpp v0, v0, v0 row_ror:2 row_mask:0xf bank_mask:0xf bound_ctrl:1
	ds_read_b128 v[194:197], v96 offset:4032
	ds_read_b128 v[202:205], v96 offset:4544
	ds_read_b128 v[206:209], v96 offset:5056
	v_add_f32_dpp v0, v0, v0 row_ror:1 row_mask:0xf bank_mask:0xf bound_ctrl:1
	v_pk_fma_f32 v[84:85], v[0:1], v[18:19], v[108:109] op_sel_hi:[0,1,1]
	v_pk_fma_f32 v[86:87], v[0:1], v[20:21], v[110:111] op_sel_hi:[0,1,1]
	v_pk_mul_f32 v[250:251], v[84:85], v[122:123]
	v_pk_fma_f32 v[220:221], v[84:85], v[118:119], v[220:221]
	v_pk_fma_f32 v[250:251], v[86:87], v[124:125], v[250:251]
	v_pk_mul_f32 v[186:187], v[84:85], v[22:23]
	v_add_f32_e32 v0, v250, v251
	v_pk_fma_f32 v[222:223], v[86:87], v[120:121], v[222:223]
	v_pk_fma_f32 v[186:187], v[86:87], v[24:25], v[186:187]
	v_add_f32_dpp v0, v0, v0 row_ror:8 row_mask:0xf bank_mask:0xf bound_ctrl:1
	s_waitcnt lgkmcnt(6)
	v_pk_mul_f32 v[224:225], v[224:225], v[214:215] op_sel_hi:[1,0]
	v_add_f32_e32 v218, v186, v187
	v_add_f32_dpp v0, v0, v0 row_ror:4 row_mask:0xf bank_mask:0xf bound_ctrl:1
	v_pk_mul_f32 v[226:227], v[226:227], v[214:215] op_sel_hi:[1,0]
	ds_read_b128 v[108:111], v96 offset:6144
	ds_read_b32 v242, v97 offset:5376
	ds_read_b128 v[14:17], v96 offset:5632
	v_add_f32_dpp v0, v0, v0 row_ror:2 row_mask:0xf bank_mask:0xf bound_ctrl:1
	ds_read_b128 v[10:13], v96 offset:5376
	ds_read_b128 v[18:21], v96 offset:5888
	ds_read_b128 v[22:25], v96 offset:6400
	v_add_f32_dpp v0, v0, v0 row_ror:1 row_mask:0xf bank_mask:0xf bound_ctrl:1
	v_pk_fma_f32 v[84:85], v[0:1], v[134:135], v[220:221] op_sel_hi:[0,1,1]
	v_pk_fma_f32 v[86:87], v[0:1], v[136:137], v[222:223] op_sel_hi:[0,1,1]
	v_pk_mul_f32 v[250:251], v[84:85], v[142:143]
	v_pk_fma_f32 v[224:225], v[84:85], v[138:139], v[224:225]
	v_pk_fma_f32 v[250:251], v[86:87], v[144:145], v[250:251]
	v_pk_mul_f32 v[186:187], v[84:85], v[230:231]
	v_add_f32_e32 v0, v250, v251
	v_pk_fma_f32 v[226:227], v[86:87], v[140:141], v[226:227]
	v_pk_fma_f32 v[186:187], v[86:87], v[232:233], v[186:187]
	v_add_f32_dpp v0, v0, v0 row_ror:8 row_mask:0xf bank_mask:0xf bound_ctrl:1
	s_waitcnt lgkmcnt(6)
	v_pk_mul_f32 v[236:237], v[236:237], v[234:235] op_sel_hi:[1,0]
	v_add_f32_e32 v219, v186, v187
	v_add_f32_dpp v0, v0, v0 row_ror:4 row_mask:0xf bank_mask:0xf bound_ctrl:1
	v_pk_mul_f32 v[238:239], v[238:239], v[234:235] op_sel_hi:[1,0]
	ds_write2st64_b32 v98, v218, v219 offset0:0 offset1:4
	ds_read_b128 v[220:223], v96 offset:7488
	ds_read_b32 v246, v97 offset:6720
	ds_read_b128 v[122:125], v96 offset:6976
	v_add_f32_dpp v0, v0, v0 row_ror:2 row_mask:0xf bank_mask:0xf bound_ctrl:1
	ds_read_b128 v[118:121], v96 offset:6720
	ds_read_b128 v[134:137], v96 offset:7232
	ds_read_b128 v[230:233], v96 offset:7744
	v_add_f32_dpp v0, v0, v0 row_ror:1 row_mask:0xf bank_mask:0xf bound_ctrl:1
	v_pk_fma_f32 v[84:85], v[0:1], v[146:147], v[224:225] op_sel_hi:[0,1,1]
	v_pk_fma_f32 v[86:87], v[0:1], v[148:149], v[226:227] op_sel_hi:[0,1,1]
	v_pk_mul_f32 v[250:251], v[84:85], v[198:199]
	v_pk_fma_f32 v[236:237], v[84:85], v[194:195], v[236:237]
	v_pk_fma_f32 v[250:251], v[86:87], v[200:201], v[250:251]
	v_pk_mul_f32 v[186:187], v[84:85], v[150:151]
	v_add_f32_e32 v0, v250, v251
	v_pk_fma_f32 v[238:239], v[86:87], v[196:197], v[238:239]
	v_pk_fma_f32 v[186:187], v[86:87], v[152:153], v[186:187]
	v_add_f32_dpp v0, v0, v0 row_ror:8 row_mask:0xf bank_mask:0xf bound_ctrl:1
	s_waitcnt lgkmcnt(7)
	v_pk_mul_f32 v[108:109], v[108:109], v[242:243] op_sel_hi:[1,0]
	v_add_f32_e32 v218, v186, v187
	v_add_f32_dpp v0, v0, v0 row_ror:4 row_mask:0xf bank_mask:0xf bound_ctrl:1
	v_pk_mul_f32 v[110:111], v[110:111], v[242:243] op_sel_hi:[1,0]
	ds_read_b128 v[224:227], v96 offset:8832
	ds_read_b32 v214, v97 offset:8064
	ds_read_b128 v[142:145], v96 offset:8320
	v_add_f32_dpp v0, v0, v0 row_ror:2 row_mask:0xf bank_mask:0xf bound_ctrl:1
	ds_read_b128 v[138:141], v96 offset:8064
	ds_read_b128 v[146:149], v96 offset:8576
	ds_read_b128 v[150:153], v96 offset:9088
	v_add_f32_dpp v0, v0, v0 row_ror:1 row_mask:0xf bank_mask:0xf bound_ctrl:1
	v_pk_fma_f32 v[84:85], v[0:1], v[202:203], v[236:237] op_sel_hi:[0,1,1]
	v_pk_fma_f32 v[86:87], v[0:1], v[204:205], v[238:239] op_sel_hi:[0,1,1]
	v_pk_mul_f32 v[250:251], v[84:85], v[14:15]
	v_pk_fma_f32 v[108:109], v[84:85], v[10:11], v[108:109]
	v_pk_fma_f32 v[250:251], v[86:87], v[16:17], v[250:251]
	v_pk_mul_f32 v[186:187], v[84:85], v[206:207]
	v_add_f32_e32 v0, v250, v251
	v_pk_fma_f32 v[110:111], v[86:87], v[12:13], v[110:111]
	v_pk_fma_f32 v[186:187], v[86:87], v[208:209], v[186:187]
	v_add_f32_dpp v0, v0, v0 row_ror:8 row_mask:0xf bank_mask:0xf bound_ctrl:1
	s_waitcnt lgkmcnt(6)
	v_pk_mul_f32 v[220:221], v[220:221], v[246:247] op_sel_hi:[1,0]
	v_add_f32_e32 v219, v186, v187
	v_add_f32_dpp v0, v0, v0 row_ror:4 row_mask:0xf bank_mask:0xf bound_ctrl:1
	v_pk_mul_f32 v[222:223], v[222:223], v[246:247] op_sel_hi:[1,0]
	ds_write2st64_b32 v98, v218, v219 offset0:8 offset1:12
	ds_read_b128 v[236:239], v96 offset:10176
	ds_read_b32 v234, v97 offset:9408
	ds_read_b128 v[198:201], v96 offset:9664
	v_add_f32_dpp v0, v0, v0 row_ror:2 row_mask:0xf bank_mask:0xf bound_ctrl:1
	ds_read_b128 v[194:197], v96 offset:9408
	ds_read_b128 v[202:205], v96 offset:9920
	ds_read_b128 v[206:209], v96 offset:10432
	v_add_f32_dpp v0, v0, v0 row_ror:1 row_mask:0xf bank_mask:0xf bound_ctrl:1
	v_pk_fma_f32 v[84:85], v[0:1], v[18:19], v[108:109] op_sel_hi:[0,1,1]
	v_pk_fma_f32 v[86:87], v[0:1], v[20:21], v[110:111] op_sel_hi:[0,1,1]
	v_pk_mul_f32 v[250:251], v[84:85], v[122:123]
	v_pk_fma_f32 v[220:221], v[84:85], v[118:119], v[220:221]
	v_pk_fma_f32 v[250:251], v[86:87], v[124:125], v[250:251]
	v_pk_mul_f32 v[186:187], v[84:85], v[22:23]
	v_add_f32_e32 v0, v250, v251
	v_pk_fma_f32 v[222:223], v[86:87], v[120:121], v[222:223]
	v_pk_fma_f32 v[186:187], v[86:87], v[24:25], v[186:187]
	v_add_f32_dpp v0, v0, v0 row_ror:8 row_mask:0xf bank_mask:0xf bound_ctrl:1
	s_waitcnt lgkmcnt(7)
	v_pk_mul_f32 v[224:225], v[224:225], v[214:215] op_sel_hi:[1,0]
	v_add_f32_e32 v218, v186, v187
	v_add_f32_dpp v0, v0, v0 row_ror:4 row_mask:0xf bank_mask:0xf bound_ctrl:1
	v_pk_mul_f32 v[226:227], v[226:227], v[214:215] op_sel_hi:[1,0]
	ds_read_b128 v[108:111], v96 offset:11520
	ds_read_b32 v242, v97 offset:10752
	ds_read_b128 v[14:17], v96 offset:11008
	v_add_f32_dpp v0, v0, v0 row_ror:2 row_mask:0xf bank_mask:0xf bound_ctrl:1
	ds_read_b128 v[10:13], v96 offset:10752
	ds_read_b128 v[18:21], v96 offset:11264
	ds_read_b128 v[22:25], v96 offset:11776
	v_add_f32_dpp v0, v0, v0 row_ror:1 row_mask:0xf bank_mask:0xf bound_ctrl:1
	v_pk_fma_f32 v[84:85], v[0:1], v[134:135], v[220:221] op_sel_hi:[0,1,1]
	v_pk_fma_f32 v[86:87], v[0:1], v[136:137], v[222:223] op_sel_hi:[0,1,1]
	v_pk_mul_f32 v[250:251], v[84:85], v[142:143]
	v_pk_fma_f32 v[224:225], v[84:85], v[138:139], v[224:225]
	v_pk_fma_f32 v[250:251], v[86:87], v[144:145], v[250:251]
	v_pk_mul_f32 v[186:187], v[84:85], v[230:231]
	v_add_f32_e32 v0, v250, v251
	v_pk_fma_f32 v[226:227], v[86:87], v[140:141], v[226:227]
	v_pk_fma_f32 v[186:187], v[86:87], v[232:233], v[186:187]
	v_add_f32_dpp v0, v0, v0 row_ror:8 row_mask:0xf bank_mask:0xf bound_ctrl:1
	s_waitcnt lgkmcnt(6)
	v_pk_mul_f32 v[236:237], v[236:237], v[234:235] op_sel_hi:[1,0]
	v_add_f32_e32 v219, v186, v187
	v_add_f32_dpp v0, v0, v0 row_ror:4 row_mask:0xf bank_mask:0xf bound_ctrl:1
	v_pk_mul_f32 v[238:239], v[238:239], v[234:235] op_sel_hi:[1,0]
	ds_write2st64_b32 v98, v218, v219 offset0:16 offset1:20
	ds_read_b128 v[220:223], v96 offset:12864
	ds_read_b32 v246, v97 offset:12096
	ds_read_b128 v[122:125], v96 offset:12352
	v_add_f32_dpp v0, v0, v0 row_ror:2 row_mask:0xf bank_mask:0xf bound_ctrl:1
	ds_read_b128 v[118:121], v96 offset:12096
	ds_read_b128 v[134:137], v96 offset:12608
	ds_read_b128 v[230:233], v96 offset:13120
	v_add_f32_dpp v0, v0, v0 row_ror:1 row_mask:0xf bank_mask:0xf bound_ctrl:1
	v_pk_fma_f32 v[84:85], v[0:1], v[146:147], v[224:225] op_sel_hi:[0,1,1]
	v_pk_fma_f32 v[86:87], v[0:1], v[148:149], v[226:227] op_sel_hi:[0,1,1]
	v_pk_mul_f32 v[250:251], v[84:85], v[198:199]
	v_pk_fma_f32 v[236:237], v[84:85], v[194:195], v[236:237]
	v_pk_fma_f32 v[250:251], v[86:87], v[200:201], v[250:251]
	v_pk_mul_f32 v[186:187], v[84:85], v[150:151]
	v_add_f32_e32 v0, v250, v251
	v_pk_fma_f32 v[238:239], v[86:87], v[196:197], v[238:239]
	v_pk_fma_f32 v[186:187], v[86:87], v[152:153], v[186:187]
	v_add_f32_dpp v0, v0, v0 row_ror:8 row_mask:0xf bank_mask:0xf bound_ctrl:1
	s_waitcnt lgkmcnt(7)
	v_pk_mul_f32 v[108:109], v[108:109], v[242:243] op_sel_hi:[1,0]
	v_add_f32_e32 v218, v186, v187
	v_add_f32_dpp v0, v0, v0 row_ror:4 row_mask:0xf bank_mask:0xf bound_ctrl:1
	v_pk_mul_f32 v[110:111], v[110:111], v[242:243] op_sel_hi:[1,0]
	ds_read_b128 v[224:227], v96 offset:14208
	ds_read_b32 v214, v97 offset:13440
	ds_read_b128 v[142:145], v96 offset:13696
	v_add_f32_dpp v0, v0, v0 row_ror:2 row_mask:0xf bank_mask:0xf bound_ctrl:1
	ds_read_b128 v[138:141], v96 offset:13440
	ds_read_b128 v[146:149], v96 offset:13952
	ds_read_b128 v[150:153], v96 offset:14464
	v_add_f32_dpp v0, v0, v0 row_ror:1 row_mask:0xf bank_mask:0xf bound_ctrl:1
	v_pk_fma_f32 v[84:85], v[0:1], v[202:203], v[236:237] op_sel_hi:[0,1,1]
	v_pk_fma_f32 v[86:87], v[0:1], v[204:205], v[238:239] op_sel_hi:[0,1,1]
	v_pk_mul_f32 v[250:251], v[84:85], v[14:15]
	v_pk_fma_f32 v[108:109], v[84:85], v[10:11], v[108:109]
	v_pk_fma_f32 v[250:251], v[86:87], v[16:17], v[250:251]
	v_pk_mul_f32 v[186:187], v[84:85], v[206:207]
	v_add_f32_e32 v0, v250, v251
	v_pk_fma_f32 v[110:111], v[86:87], v[12:13], v[110:111]
	v_pk_fma_f32 v[186:187], v[86:87], v[208:209], v[186:187]
	v_add_f32_dpp v0, v0, v0 row_ror:8 row_mask:0xf bank_mask:0xf bound_ctrl:1
	s_waitcnt lgkmcnt(6)
	v_pk_mul_f32 v[220:221], v[220:221], v[246:247] op_sel_hi:[1,0]
	v_add_f32_e32 v219, v186, v187
	v_add_f32_dpp v0, v0, v0 row_ror:4 row_mask:0xf bank_mask:0xf bound_ctrl:1
	v_pk_mul_f32 v[222:223], v[222:223], v[246:247] op_sel_hi:[1,0]
	ds_write2st64_b32 v98, v218, v219 offset0:24 offset1:28
	ds_read_b128 v[236:239], v96 offset:15552
	ds_read_b32 v234, v97 offset:14784
	ds_read_b128 v[198:201], v96 offset:15040
	v_add_f32_dpp v0, v0, v0 row_ror:2 row_mask:0xf bank_mask:0xf bound_ctrl:1
	ds_read_b128 v[194:197], v96 offset:14784
	ds_read_b128 v[202:205], v96 offset:15296
	ds_read_b128 v[206:209], v96 offset:15808
	v_add_f32_dpp v0, v0, v0 row_ror:1 row_mask:0xf bank_mask:0xf bound_ctrl:1
	v_pk_fma_f32 v[84:85], v[0:1], v[18:19], v[108:109] op_sel_hi:[0,1,1]
	v_pk_fma_f32 v[86:87], v[0:1], v[20:21], v[110:111] op_sel_hi:[0,1,1]
	v_pk_mul_f32 v[250:251], v[84:85], v[122:123]
	v_pk_fma_f32 v[220:221], v[84:85], v[118:119], v[220:221]
	v_pk_fma_f32 v[250:251], v[86:87], v[124:125], v[250:251]
	v_pk_mul_f32 v[186:187], v[84:85], v[22:23]
	v_add_f32_e32 v0, v250, v251
	v_pk_fma_f32 v[222:223], v[86:87], v[120:121], v[222:223]
	v_pk_fma_f32 v[186:187], v[86:87], v[24:25], v[186:187]
	v_add_f32_dpp v0, v0, v0 row_ror:8 row_mask:0xf bank_mask:0xf bound_ctrl:1
	s_waitcnt lgkmcnt(7)
	v_pk_mul_f32 v[224:225], v[224:225], v[214:215] op_sel_hi:[1,0]
	v_add_f32_e32 v218, v186, v187
	v_add_f32_dpp v0, v0, v0 row_ror:4 row_mask:0xf bank_mask:0xf bound_ctrl:1
	v_pk_mul_f32 v[226:227], v[226:227], v[214:215] op_sel_hi:[1,0]
	ds_read_b128 v[108:111], v96 offset:16896
	ds_read_b32 v242, v97 offset:16128
	ds_read_b128 v[14:17], v96 offset:16384
	v_add_f32_dpp v0, v0, v0 row_ror:2 row_mask:0xf bank_mask:0xf bound_ctrl:1
	ds_read_b128 v[10:13], v96 offset:16128
	ds_read_b128 v[18:21], v96 offset:16640
	ds_read_b128 v[22:25], v96 offset:17152
	v_add_f32_dpp v0, v0, v0 row_ror:1 row_mask:0xf bank_mask:0xf bound_ctrl:1
	v_pk_fma_f32 v[84:85], v[0:1], v[134:135], v[220:221] op_sel_hi:[0,1,1]
	v_pk_fma_f32 v[86:87], v[0:1], v[136:137], v[222:223] op_sel_hi:[0,1,1]
	v_pk_mul_f32 v[250:251], v[84:85], v[142:143]
	v_pk_fma_f32 v[224:225], v[84:85], v[138:139], v[224:225]
	v_pk_fma_f32 v[250:251], v[86:87], v[144:145], v[250:251]
	v_pk_mul_f32 v[186:187], v[84:85], v[230:231]
	v_add_f32_e32 v0, v250, v251
	v_pk_fma_f32 v[226:227], v[86:87], v[140:141], v[226:227]
	v_pk_fma_f32 v[186:187], v[86:87], v[232:233], v[186:187]
	v_add_f32_dpp v0, v0, v0 row_ror:8 row_mask:0xf bank_mask:0xf bound_ctrl:1
	s_waitcnt lgkmcnt(6)
	v_pk_mul_f32 v[236:237], v[236:237], v[234:235] op_sel_hi:[1,0]
	v_add_f32_e32 v219, v186, v187
	v_add_f32_dpp v0, v0, v0 row_ror:4 row_mask:0xf bank_mask:0xf bound_ctrl:1
	v_pk_mul_f32 v[238:239], v[238:239], v[234:235] op_sel_hi:[1,0]
	ds_write2st64_b32 v98, v218, v219 offset0:32 offset1:36
	ds_read_b128 v[220:223], v96 offset:18240
	ds_read_b32 v246, v97 offset:17472
	ds_read_b128 v[122:125], v96 offset:17728
	v_add_f32_dpp v0, v0, v0 row_ror:2 row_mask:0xf bank_mask:0xf bound_ctrl:1
	ds_read_b128 v[118:121], v96 offset:17472
	ds_read_b128 v[134:137], v96 offset:17984
	ds_read_b128 v[230:233], v96 offset:18496
	v_add_f32_dpp v0, v0, v0 row_ror:1 row_mask:0xf bank_mask:0xf bound_ctrl:1
	v_pk_fma_f32 v[84:85], v[0:1], v[146:147], v[224:225] op_sel_hi:[0,1,1]
	v_pk_fma_f32 v[86:87], v[0:1], v[148:149], v[226:227] op_sel_hi:[0,1,1]
	v_pk_mul_f32 v[250:251], v[84:85], v[198:199]
	v_pk_fma_f32 v[236:237], v[84:85], v[194:195], v[236:237]
	v_pk_fma_f32 v[250:251], v[86:87], v[200:201], v[250:251]
	v_pk_mul_f32 v[186:187], v[84:85], v[150:151]
	v_add_f32_e32 v0, v250, v251
	v_pk_fma_f32 v[238:239], v[86:87], v[196:197], v[238:239]
	v_pk_fma_f32 v[186:187], v[86:87], v[152:153], v[186:187]
	v_add_f32_dpp v0, v0, v0 row_ror:8 row_mask:0xf bank_mask:0xf bound_ctrl:1
	s_waitcnt lgkmcnt(7)
	v_pk_mul_f32 v[108:109], v[108:109], v[242:243] op_sel_hi:[1,0]
	v_add_f32_e32 v218, v186, v187
	v_add_f32_dpp v0, v0, v0 row_ror:4 row_mask:0xf bank_mask:0xf bound_ctrl:1
	v_pk_mul_f32 v[110:111], v[110:111], v[242:243] op_sel_hi:[1,0]
	ds_read_b128 v[224:227], v96 offset:19584
	ds_read_b32 v214, v97 offset:18816
	ds_read_b128 v[142:145], v96 offset:19072
	v_add_f32_dpp v0, v0, v0 row_ror:2 row_mask:0xf bank_mask:0xf bound_ctrl:1
	ds_read_b128 v[138:141], v96 offset:18816
	ds_read_b128 v[146:149], v96 offset:19328
	ds_read_b128 v[150:153], v96 offset:19840
	v_add_f32_dpp v0, v0, v0 row_ror:1 row_mask:0xf bank_mask:0xf bound_ctrl:1
	v_pk_fma_f32 v[84:85], v[0:1], v[202:203], v[236:237] op_sel_hi:[0,1,1]
	v_pk_fma_f32 v[86:87], v[0:1], v[204:205], v[238:239] op_sel_hi:[0,1,1]
	v_pk_mul_f32 v[250:251], v[84:85], v[14:15]
	v_pk_fma_f32 v[108:109], v[84:85], v[10:11], v[108:109]
	v_pk_fma_f32 v[250:251], v[86:87], v[16:17], v[250:251]
	v_pk_mul_f32 v[186:187], v[84:85], v[206:207]
	v_add_f32_e32 v0, v250, v251
	v_pk_fma_f32 v[110:111], v[86:87], v[12:13], v[110:111]
	v_pk_fma_f32 v[186:187], v[86:87], v[208:209], v[186:187]
	v_add_f32_dpp v0, v0, v0 row_ror:8 row_mask:0xf bank_mask:0xf bound_ctrl:1
	s_waitcnt lgkmcnt(6)
	v_pk_mul_f32 v[220:221], v[220:221], v[246:247] op_sel_hi:[1,0]
	v_add_f32_e32 v219, v186, v187
	v_add_f32_dpp v0, v0, v0 row_ror:4 row_mask:0xf bank_mask:0xf bound_ctrl:1
	v_pk_mul_f32 v[222:223], v[222:223], v[246:247] op_sel_hi:[1,0]
	ds_write2st64_b32 v98, v218, v219 offset0:40 offset1:44
	ds_read_b128 v[236:239], v96 offset:20928
	ds_read_b32 v234, v97 offset:20160
	ds_read_b128 v[198:201], v96 offset:20416
	v_add_f32_dpp v0, v0, v0 row_ror:2 row_mask:0xf bank_mask:0xf bound_ctrl:1
	ds_read_b128 v[194:197], v96 offset:20160
	ds_read_b128 v[202:205], v96 offset:20672
	ds_read_b128 v[206:209], v96 offset:21184
	v_add_f32_dpp v0, v0, v0 row_ror:1 row_mask:0xf bank_mask:0xf bound_ctrl:1
	v_pk_fma_f32 v[84:85], v[0:1], v[18:19], v[108:109] op_sel_hi:[0,1,1]
	v_pk_fma_f32 v[86:87], v[0:1], v[20:21], v[110:111] op_sel_hi:[0,1,1]
	v_pk_mul_f32 v[250:251], v[84:85], v[122:123]
	v_pk_fma_f32 v[220:221], v[84:85], v[118:119], v[220:221]
	v_pk_fma_f32 v[250:251], v[86:87], v[124:125], v[250:251]
	v_pk_mul_f32 v[186:187], v[84:85], v[22:23]
	v_add_f32_e32 v0, v250, v251
	v_pk_fma_f32 v[222:223], v[86:87], v[120:121], v[222:223]
	v_pk_fma_f32 v[186:187], v[86:87], v[24:25], v[186:187]
	v_add_f32_dpp v0, v0, v0 row_ror:8 row_mask:0xf bank_mask:0xf bound_ctrl:1
	s_waitcnt lgkmcnt(7)
	v_pk_mul_f32 v[224:225], v[224:225], v[214:215] op_sel_hi:[1,0]
	v_add_f32_e32 v218, v186, v187
	v_add_f32_dpp v0, v0, v0 row_ror:4 row_mask:0xf bank_mask:0xf bound_ctrl:1
	v_pk_mul_f32 v[226:227], v[226:227], v[214:215] op_sel_hi:[1,0]
	ds_read_b128 v[108:111], v96 offset:22272
	ds_read_b32 v242, v97 offset:21504
	ds_read_b128 v[14:17], v96 offset:21760
	v_add_f32_dpp v0, v0, v0 row_ror:2 row_mask:0xf bank_mask:0xf bound_ctrl:1
	ds_read_b128 v[10:13], v96 offset:21504
	ds_read_b128 v[18:21], v96 offset:22016
	ds_read_b128 v[22:25], v96 offset:22528
	v_add_f32_dpp v0, v0, v0 row_ror:1 row_mask:0xf bank_mask:0xf bound_ctrl:1
	v_pk_fma_f32 v[84:85], v[0:1], v[134:135], v[220:221] op_sel_hi:[0,1,1]
	v_pk_fma_f32 v[86:87], v[0:1], v[136:137], v[222:223] op_sel_hi:[0,1,1]
	v_pk_mul_f32 v[250:251], v[84:85], v[142:143]
	v_pk_fma_f32 v[224:225], v[84:85], v[138:139], v[224:225]
	v_pk_fma_f32 v[250:251], v[86:87], v[144:145], v[250:251]
	v_pk_mul_f32 v[186:187], v[84:85], v[230:231]
	v_add_f32_e32 v0, v250, v251
	v_pk_fma_f32 v[226:227], v[86:87], v[140:141], v[226:227]
	v_pk_fma_f32 v[186:187], v[86:87], v[232:233], v[186:187]
	v_add_f32_dpp v0, v0, v0 row_ror:8 row_mask:0xf bank_mask:0xf bound_ctrl:1
	s_waitcnt lgkmcnt(6)
	v_pk_mul_f32 v[236:237], v[236:237], v[234:235] op_sel_hi:[1,0]
	v_add_f32_e32 v219, v186, v187
	v_add_f32_dpp v0, v0, v0 row_ror:4 row_mask:0xf bank_mask:0xf bound_ctrl:1
	v_pk_mul_f32 v[238:239], v[238:239], v[234:235] op_sel_hi:[1,0]
	ds_write2st64_b32 v98, v218, v219 offset0:48 offset1:52
	ds_read_b128 v[220:223], v96 offset:23616
	ds_read_b32 v246, v97 offset:22848
	ds_read_b128 v[122:125], v96 offset:23104
	v_add_f32_dpp v0, v0, v0 row_ror:2 row_mask:0xf bank_mask:0xf bound_ctrl:1
	ds_read_b128 v[118:121], v96 offset:22848
	ds_read_b128 v[134:137], v96 offset:23360
	ds_read_b128 v[230:233], v96 offset:23872
	v_add_f32_dpp v0, v0, v0 row_ror:1 row_mask:0xf bank_mask:0xf bound_ctrl:1
	v_pk_fma_f32 v[84:85], v[0:1], v[146:147], v[224:225] op_sel_hi:[0,1,1]
	v_pk_fma_f32 v[86:87], v[0:1], v[148:149], v[226:227] op_sel_hi:[0,1,1]
	v_pk_mul_f32 v[250:251], v[84:85], v[198:199]
	v_pk_fma_f32 v[236:237], v[84:85], v[194:195], v[236:237]
	v_pk_fma_f32 v[250:251], v[86:87], v[200:201], v[250:251]
	v_pk_mul_f32 v[186:187], v[84:85], v[150:151]
	v_add_f32_e32 v0, v250, v251
	v_pk_fma_f32 v[238:239], v[86:87], v[196:197], v[238:239]
	v_pk_fma_f32 v[186:187], v[86:87], v[152:153], v[186:187]
	v_add_f32_dpp v0, v0, v0 row_ror:8 row_mask:0xf bank_mask:0xf bound_ctrl:1
	s_waitcnt lgkmcnt(7)
	v_pk_mul_f32 v[108:109], v[108:109], v[242:243] op_sel_hi:[1,0]
	v_add_f32_e32 v218, v186, v187
	v_add_f32_dpp v0, v0, v0 row_ror:4 row_mask:0xf bank_mask:0xf bound_ctrl:1
	v_pk_mul_f32 v[110:111], v[110:111], v[242:243] op_sel_hi:[1,0]
	ds_read_b128 v[224:227], v96 offset:24960
	ds_read_b32 v214, v97 offset:24192
	ds_read_b128 v[142:145], v96 offset:24448
	v_add_f32_dpp v0, v0, v0 row_ror:2 row_mask:0xf bank_mask:0xf bound_ctrl:1
	ds_read_b128 v[138:141], v96 offset:24192
	ds_read_b128 v[146:149], v96 offset:24704
	ds_read_b128 v[150:153], v96 offset:25216
	v_add_f32_dpp v0, v0, v0 row_ror:1 row_mask:0xf bank_mask:0xf bound_ctrl:1
	v_pk_fma_f32 v[84:85], v[0:1], v[202:203], v[236:237] op_sel_hi:[0,1,1]
	v_pk_fma_f32 v[86:87], v[0:1], v[204:205], v[238:239] op_sel_hi:[0,1,1]
	v_pk_mul_f32 v[250:251], v[84:85], v[14:15]
	v_pk_fma_f32 v[108:109], v[84:85], v[10:11], v[108:109]
	v_pk_fma_f32 v[250:251], v[86:87], v[16:17], v[250:251]
	v_pk_mul_f32 v[186:187], v[84:85], v[206:207]
	v_add_f32_e32 v0, v250, v251
	v_pk_fma_f32 v[110:111], v[86:87], v[12:13], v[110:111]
	v_pk_fma_f32 v[186:187], v[86:87], v[208:209], v[186:187]
	v_add_f32_dpp v0, v0, v0 row_ror:8 row_mask:0xf bank_mask:0xf bound_ctrl:1
	s_waitcnt lgkmcnt(6)
	v_pk_mul_f32 v[220:221], v[220:221], v[246:247] op_sel_hi:[1,0]
	v_add_f32_e32 v219, v186, v187
	v_add_f32_dpp v0, v0, v0 row_ror:4 row_mask:0xf bank_mask:0xf bound_ctrl:1
	v_pk_mul_f32 v[222:223], v[222:223], v[246:247] op_sel_hi:[1,0]
	ds_write2st64_b32 v98, v218, v219 offset0:56 offset1:60
	ds_read_b128 v[236:239], v96 offset:26304
	ds_read_b32 v234, v97 offset:25536
	ds_read_b128 v[198:201], v96 offset:25792
	v_add_f32_dpp v0, v0, v0 row_ror:2 row_mask:0xf bank_mask:0xf bound_ctrl:1
	ds_read_b128 v[194:197], v96 offset:25536
	ds_read_b128 v[202:205], v96 offset:26048
	ds_read_b128 v[206:209], v96 offset:26560
	v_add_f32_dpp v0, v0, v0 row_ror:1 row_mask:0xf bank_mask:0xf bound_ctrl:1
	v_pk_fma_f32 v[84:85], v[0:1], v[18:19], v[108:109] op_sel_hi:[0,1,1]
	v_pk_fma_f32 v[86:87], v[0:1], v[20:21], v[110:111] op_sel_hi:[0,1,1]
	v_pk_mul_f32 v[250:251], v[84:85], v[122:123]
	v_pk_fma_f32 v[220:221], v[84:85], v[118:119], v[220:221]
	v_pk_fma_f32 v[250:251], v[86:87], v[124:125], v[250:251]
	v_pk_mul_f32 v[186:187], v[84:85], v[22:23]
	v_add_f32_e32 v0, v250, v251
	v_pk_fma_f32 v[222:223], v[86:87], v[120:121], v[222:223]
	v_pk_fma_f32 v[186:187], v[86:87], v[24:25], v[186:187]
	v_add_f32_dpp v0, v0, v0 row_ror:8 row_mask:0xf bank_mask:0xf bound_ctrl:1
	s_waitcnt lgkmcnt(7)
	v_pk_mul_f32 v[224:225], v[224:225], v[214:215] op_sel_hi:[1,0]
	v_add_f32_e32 v218, v186, v187
	v_add_f32_dpp v0, v0, v0 row_ror:4 row_mask:0xf bank_mask:0xf bound_ctrl:1
	v_pk_mul_f32 v[226:227], v[226:227], v[214:215] op_sel_hi:[1,0]
	ds_read_b128 v[108:111], v96 offset:27648
	ds_read_b32 v242, v97 offset:26880
	ds_read_b128 v[14:17], v96 offset:27136
	v_add_f32_dpp v0, v0, v0 row_ror:2 row_mask:0xf bank_mask:0xf bound_ctrl:1
	ds_read_b128 v[10:13], v96 offset:26880
	ds_read_b128 v[18:21], v96 offset:27392
	ds_read_b128 v[22:25], v96 offset:27904
	v_add_f32_dpp v0, v0, v0 row_ror:1 row_mask:0xf bank_mask:0xf bound_ctrl:1
	v_pk_fma_f32 v[84:85], v[0:1], v[134:135], v[220:221] op_sel_hi:[0,1,1]
	v_pk_fma_f32 v[86:87], v[0:1], v[136:137], v[222:223] op_sel_hi:[0,1,1]
	v_pk_mul_f32 v[250:251], v[84:85], v[142:143]
	v_pk_fma_f32 v[224:225], v[84:85], v[138:139], v[224:225]
	v_pk_fma_f32 v[250:251], v[86:87], v[144:145], v[250:251]
	v_pk_mul_f32 v[186:187], v[84:85], v[230:231]
	v_add_f32_e32 v0, v250, v251
	v_pk_fma_f32 v[226:227], v[86:87], v[140:141], v[226:227]
	v_pk_fma_f32 v[186:187], v[86:87], v[232:233], v[186:187]
	v_add_f32_dpp v0, v0, v0 row_ror:8 row_mask:0xf bank_mask:0xf bound_ctrl:1
	s_waitcnt lgkmcnt(6)
	v_pk_mul_f32 v[236:237], v[236:237], v[234:235] op_sel_hi:[1,0]
	v_add_f32_e32 v219, v186, v187
	v_add_f32_dpp v0, v0, v0 row_ror:4 row_mask:0xf bank_mask:0xf bound_ctrl:1
	v_pk_mul_f32 v[238:239], v[238:239], v[234:235] op_sel_hi:[1,0]
	ds_write2st64_b32 v98, v218, v219 offset0:64 offset1:68
	ds_read_b128 v[220:223], v96 offset:28992
	ds_read_b32 v246, v97 offset:28224
	ds_read_b128 v[122:125], v96 offset:28480
	v_add_f32_dpp v0, v0, v0 row_ror:2 row_mask:0xf bank_mask:0xf bound_ctrl:1
	ds_read_b128 v[118:121], v96 offset:28224
	ds_read_b128 v[134:137], v96 offset:28736
	ds_read_b128 v[230:233], v96 offset:29248
	v_add_f32_dpp v0, v0, v0 row_ror:1 row_mask:0xf bank_mask:0xf bound_ctrl:1
	v_pk_fma_f32 v[84:85], v[0:1], v[146:147], v[224:225] op_sel_hi:[0,1,1]
	v_pk_fma_f32 v[86:87], v[0:1], v[148:149], v[226:227] op_sel_hi:[0,1,1]
	v_pk_mul_f32 v[250:251], v[84:85], v[198:199]
	v_pk_fma_f32 v[236:237], v[84:85], v[194:195], v[236:237]
	v_pk_fma_f32 v[250:251], v[86:87], v[200:201], v[250:251]
	v_pk_mul_f32 v[186:187], v[84:85], v[150:151]
	v_add_f32_e32 v0, v250, v251
	v_pk_fma_f32 v[238:239], v[86:87], v[196:197], v[238:239]
	v_pk_fma_f32 v[186:187], v[86:87], v[152:153], v[186:187]
	v_add_f32_dpp v0, v0, v0 row_ror:8 row_mask:0xf bank_mask:0xf bound_ctrl:1
	s_waitcnt lgkmcnt(7)
	v_pk_mul_f32 v[108:109], v[108:109], v[242:243] op_sel_hi:[1,0]
	v_add_f32_e32 v218, v186, v187
	v_add_f32_dpp v0, v0, v0 row_ror:4 row_mask:0xf bank_mask:0xf bound_ctrl:1
	v_pk_mul_f32 v[110:111], v[110:111], v[242:243] op_sel_hi:[1,0]
	ds_read_b128 v[224:227], v96 offset:30336
	ds_read_b32 v214, v97 offset:29568
	ds_read_b128 v[142:145], v96 offset:29824
	v_add_f32_dpp v0, v0, v0 row_ror:2 row_mask:0xf bank_mask:0xf bound_ctrl:1
	ds_read_b128 v[138:141], v96 offset:29568
	ds_read_b128 v[146:149], v96 offset:30080
	ds_read_b128 v[150:153], v96 offset:30592
	v_add_f32_dpp v0, v0, v0 row_ror:1 row_mask:0xf bank_mask:0xf bound_ctrl:1
	v_pk_fma_f32 v[84:85], v[0:1], v[202:203], v[236:237] op_sel_hi:[0,1,1]
	v_pk_fma_f32 v[86:87], v[0:1], v[204:205], v[238:239] op_sel_hi:[0,1,1]
	v_pk_mul_f32 v[250:251], v[84:85], v[14:15]
	v_pk_fma_f32 v[108:109], v[84:85], v[10:11], v[108:109]
	v_pk_fma_f32 v[250:251], v[86:87], v[16:17], v[250:251]
	v_pk_mul_f32 v[186:187], v[84:85], v[206:207]
	v_add_f32_e32 v0, v250, v251
	v_pk_fma_f32 v[110:111], v[86:87], v[12:13], v[110:111]
	v_pk_fma_f32 v[186:187], v[86:87], v[208:209], v[186:187]
	v_add_f32_dpp v0, v0, v0 row_ror:8 row_mask:0xf bank_mask:0xf bound_ctrl:1
	s_waitcnt lgkmcnt(6)
	v_pk_mul_f32 v[220:221], v[220:221], v[246:247] op_sel_hi:[1,0]
	v_add_f32_e32 v219, v186, v187
	v_add_f32_dpp v0, v0, v0 row_ror:4 row_mask:0xf bank_mask:0xf bound_ctrl:1
	v_pk_mul_f32 v[222:223], v[222:223], v[246:247] op_sel_hi:[1,0]
	ds_write2st64_b32 v98, v218, v219 offset0:72 offset1:76
	ds_read_b128 v[236:239], v96 offset:31680
	ds_read_b32 v234, v97 offset:30912
	ds_read_b128 v[198:201], v96 offset:31168
	v_add_f32_dpp v0, v0, v0 row_ror:2 row_mask:0xf bank_mask:0xf bound_ctrl:1
	ds_read_b128 v[194:197], v96 offset:30912
	ds_read_b128 v[202:205], v96 offset:31424
	ds_read_b128 v[206:209], v96 offset:31936
	v_add_f32_dpp v0, v0, v0 row_ror:1 row_mask:0xf bank_mask:0xf bound_ctrl:1
	v_pk_fma_f32 v[84:85], v[0:1], v[18:19], v[108:109] op_sel_hi:[0,1,1]
	v_pk_fma_f32 v[86:87], v[0:1], v[20:21], v[110:111] op_sel_hi:[0,1,1]
	v_pk_mul_f32 v[250:251], v[84:85], v[122:123]
	v_pk_fma_f32 v[220:221], v[84:85], v[118:119], v[220:221]
	v_pk_fma_f32 v[250:251], v[86:87], v[124:125], v[250:251]
	v_pk_mul_f32 v[186:187], v[84:85], v[22:23]
	v_add_f32_e32 v0, v250, v251
	v_pk_fma_f32 v[222:223], v[86:87], v[120:121], v[222:223]
	v_pk_fma_f32 v[186:187], v[86:87], v[24:25], v[186:187]
	v_add_f32_dpp v0, v0, v0 row_ror:8 row_mask:0xf bank_mask:0xf bound_ctrl:1
	s_waitcnt lgkmcnt(7)
	v_pk_mul_f32 v[224:225], v[224:225], v[214:215] op_sel_hi:[1,0]
	v_add_f32_e32 v218, v186, v187
	v_add_f32_dpp v0, v0, v0 row_ror:4 row_mask:0xf bank_mask:0xf bound_ctrl:1
	v_pk_mul_f32 v[226:227], v[226:227], v[214:215] op_sel_hi:[1,0]
	ds_read_b128 v[108:111], v96 offset:33024
	ds_read_b32 v242, v97 offset:32256
	ds_read_b128 v[14:17], v96 offset:32512
	v_add_f32_dpp v0, v0, v0 row_ror:2 row_mask:0xf bank_mask:0xf bound_ctrl:1
	ds_read_b128 v[10:13], v96 offset:32256
	ds_read_b128 v[18:21], v96 offset:32768
	ds_read_b128 v[22:25], v96 offset:33280
	v_add_f32_dpp v0, v0, v0 row_ror:1 row_mask:0xf bank_mask:0xf bound_ctrl:1
	v_pk_fma_f32 v[84:85], v[0:1], v[134:135], v[220:221] op_sel_hi:[0,1,1]
	v_pk_fma_f32 v[86:87], v[0:1], v[136:137], v[222:223] op_sel_hi:[0,1,1]
	v_pk_mul_f32 v[250:251], v[84:85], v[142:143]
	v_pk_fma_f32 v[224:225], v[84:85], v[138:139], v[224:225]
	v_pk_fma_f32 v[250:251], v[86:87], v[144:145], v[250:251]
	v_pk_mul_f32 v[186:187], v[84:85], v[230:231]
	v_add_f32_e32 v0, v250, v251
	v_pk_fma_f32 v[226:227], v[86:87], v[140:141], v[226:227]
	v_pk_fma_f32 v[186:187], v[86:87], v[232:233], v[186:187]
	v_add_f32_dpp v0, v0, v0 row_ror:8 row_mask:0xf bank_mask:0xf bound_ctrl:1
	s_waitcnt lgkmcnt(6)
	v_pk_mul_f32 v[236:237], v[236:237], v[234:235] op_sel_hi:[1,0]
	v_add_f32_e32 v219, v186, v187
	v_add_f32_dpp v0, v0, v0 row_ror:4 row_mask:0xf bank_mask:0xf bound_ctrl:1
	v_pk_mul_f32 v[238:239], v[238:239], v[234:235] op_sel_hi:[1,0]
	ds_write2st64_b32 v98, v218, v219 offset0:80 offset1:84
	ds_read_b128 v[220:223], v96 offset:34368
	ds_read_b32 v246, v97 offset:33600
	ds_read_b128 v[122:125], v96 offset:33856
	v_add_f32_dpp v0, v0, v0 row_ror:2 row_mask:0xf bank_mask:0xf bound_ctrl:1
	ds_read_b128 v[118:121], v96 offset:33600
	ds_read_b128 v[134:137], v96 offset:34112
	ds_read_b128 v[230:233], v96 offset:34624
	v_add_f32_dpp v0, v0, v0 row_ror:1 row_mask:0xf bank_mask:0xf bound_ctrl:1
	v_pk_fma_f32 v[84:85], v[0:1], v[146:147], v[224:225] op_sel_hi:[0,1,1]
	v_pk_fma_f32 v[86:87], v[0:1], v[148:149], v[226:227] op_sel_hi:[0,1,1]
	v_pk_mul_f32 v[250:251], v[84:85], v[198:199]
	v_pk_fma_f32 v[236:237], v[84:85], v[194:195], v[236:237]
	v_pk_fma_f32 v[250:251], v[86:87], v[200:201], v[250:251]
	v_pk_mul_f32 v[186:187], v[84:85], v[150:151]
	v_add_f32_e32 v0, v250, v251
	v_pk_fma_f32 v[238:239], v[86:87], v[196:197], v[238:239]
	v_pk_fma_f32 v[186:187], v[86:87], v[152:153], v[186:187]
	v_add_f32_dpp v0, v0, v0 row_ror:8 row_mask:0xf bank_mask:0xf bound_ctrl:1
	s_waitcnt lgkmcnt(7)
	v_pk_mul_f32 v[108:109], v[108:109], v[242:243] op_sel_hi:[1,0]
	v_add_f32_e32 v218, v186, v187
	v_add_f32_dpp v0, v0, v0 row_ror:4 row_mask:0xf bank_mask:0xf bound_ctrl:1
	v_pk_mul_f32 v[110:111], v[110:111], v[242:243] op_sel_hi:[1,0]
	ds_read_b128 v[224:227], v96 offset:35712
	ds_read_b32 v214, v97 offset:34944
	ds_read_b128 v[142:145], v96 offset:35200
	v_add_f32_dpp v0, v0, v0 row_ror:2 row_mask:0xf bank_mask:0xf bound_ctrl:1
	ds_read_b128 v[138:141], v96 offset:34944
	ds_read_b128 v[146:149], v96 offset:35456
	ds_read_b128 v[150:153], v96 offset:35968
	v_add_f32_dpp v0, v0, v0 row_ror:1 row_mask:0xf bank_mask:0xf bound_ctrl:1
	v_pk_fma_f32 v[84:85], v[0:1], v[202:203], v[236:237] op_sel_hi:[0,1,1]
	v_pk_fma_f32 v[86:87], v[0:1], v[204:205], v[238:239] op_sel_hi:[0,1,1]
	v_pk_mul_f32 v[250:251], v[84:85], v[14:15]
	v_pk_fma_f32 v[108:109], v[84:85], v[10:11], v[108:109]
	v_pk_fma_f32 v[250:251], v[86:87], v[16:17], v[250:251]
	v_pk_mul_f32 v[186:187], v[84:85], v[206:207]
	v_add_f32_e32 v0, v250, v251
	v_pk_fma_f32 v[110:111], v[86:87], v[12:13], v[110:111]
	v_pk_fma_f32 v[186:187], v[86:87], v[208:209], v[186:187]
	v_add_f32_dpp v0, v0, v0 row_ror:8 row_mask:0xf bank_mask:0xf bound_ctrl:1
	s_waitcnt lgkmcnt(6)
	v_pk_mul_f32 v[220:221], v[220:221], v[246:247] op_sel_hi:[1,0]
	v_add_f32_e32 v219, v186, v187
	v_add_f32_dpp v0, v0, v0 row_ror:4 row_mask:0xf bank_mask:0xf bound_ctrl:1
	v_pk_mul_f32 v[222:223], v[222:223], v[246:247] op_sel_hi:[1,0]
	ds_write2st64_b32 v98, v218, v219 offset0:88 offset1:92
	ds_read_b128 v[236:239], v96 offset:37056
	ds_read_b32 v234, v97 offset:36288
	ds_read_b128 v[198:201], v96 offset:36544
	v_add_f32_dpp v0, v0, v0 row_ror:2 row_mask:0xf bank_mask:0xf bound_ctrl:1
	ds_read_b128 v[194:197], v96 offset:36288
	ds_read_b128 v[202:205], v96 offset:36800
	ds_read_b128 v[206:209], v96 offset:37312
	v_add_f32_dpp v0, v0, v0 row_ror:1 row_mask:0xf bank_mask:0xf bound_ctrl:1
	v_pk_fma_f32 v[84:85], v[0:1], v[18:19], v[108:109] op_sel_hi:[0,1,1]
	v_pk_fma_f32 v[86:87], v[0:1], v[20:21], v[110:111] op_sel_hi:[0,1,1]
	v_pk_mul_f32 v[250:251], v[84:85], v[122:123]
	v_pk_fma_f32 v[220:221], v[84:85], v[118:119], v[220:221]
	v_pk_fma_f32 v[250:251], v[86:87], v[124:125], v[250:251]
	v_pk_mul_f32 v[186:187], v[84:85], v[22:23]
	v_add_f32_e32 v0, v250, v251
	v_pk_fma_f32 v[222:223], v[86:87], v[120:121], v[222:223]
	v_pk_fma_f32 v[186:187], v[86:87], v[24:25], v[186:187]
	v_add_f32_dpp v0, v0, v0 row_ror:8 row_mask:0xf bank_mask:0xf bound_ctrl:1
	s_waitcnt lgkmcnt(7)
	v_pk_mul_f32 v[224:225], v[224:225], v[214:215] op_sel_hi:[1,0]
	v_add_f32_e32 v218, v186, v187
	v_add_f32_dpp v0, v0, v0 row_ror:4 row_mask:0xf bank_mask:0xf bound_ctrl:1
	v_pk_mul_f32 v[226:227], v[226:227], v[214:215] op_sel_hi:[1,0]
	ds_read_b128 v[108:111], v96 offset:38400
	ds_read_b32 v242, v97 offset:37632
	ds_read_b128 v[14:17], v96 offset:37888
	v_add_f32_dpp v0, v0, v0 row_ror:2 row_mask:0xf bank_mask:0xf bound_ctrl:1
	ds_read_b128 v[10:13], v96 offset:37632
	ds_read_b128 v[18:21], v96 offset:38144
	ds_read_b128 v[22:25], v96 offset:38656
	v_add_f32_dpp v0, v0, v0 row_ror:1 row_mask:0xf bank_mask:0xf bound_ctrl:1
	v_pk_fma_f32 v[84:85], v[0:1], v[134:135], v[220:221] op_sel_hi:[0,1,1]
	v_pk_fma_f32 v[86:87], v[0:1], v[136:137], v[222:223] op_sel_hi:[0,1,1]
	v_pk_mul_f32 v[250:251], v[84:85], v[142:143]
	v_pk_fma_f32 v[224:225], v[84:85], v[138:139], v[224:225]
	v_pk_fma_f32 v[250:251], v[86:87], v[144:145], v[250:251]
	v_pk_mul_f32 v[186:187], v[84:85], v[230:231]
	v_add_f32_e32 v0, v250, v251
	v_pk_fma_f32 v[226:227], v[86:87], v[140:141], v[226:227]
	v_pk_fma_f32 v[186:187], v[86:87], v[232:233], v[186:187]
	v_add_f32_dpp v0, v0, v0 row_ror:8 row_mask:0xf bank_mask:0xf bound_ctrl:1
	s_waitcnt lgkmcnt(6)
	v_pk_mul_f32 v[236:237], v[236:237], v[234:235] op_sel_hi:[1,0]
	v_add_f32_e32 v219, v186, v187
	v_add_f32_dpp v0, v0, v0 row_ror:4 row_mask:0xf bank_mask:0xf bound_ctrl:1
	v_pk_mul_f32 v[238:239], v[238:239], v[234:235] op_sel_hi:[1,0]
	ds_write2st64_b32 v98, v218, v219 offset0:96 offset1:100
	ds_read_b128 v[220:223], v96 offset:39744
	ds_read_b32 v246, v97 offset:38976
	ds_read_b128 v[122:125], v96 offset:39232
	v_add_f32_dpp v0, v0, v0 row_ror:2 row_mask:0xf bank_mask:0xf bound_ctrl:1
	ds_read_b128 v[118:121], v96 offset:38976
	ds_read_b128 v[134:137], v96 offset:39488
	ds_read_b128 v[230:233], v96 offset:40000
	v_add_f32_dpp v0, v0, v0 row_ror:1 row_mask:0xf bank_mask:0xf bound_ctrl:1
	v_pk_fma_f32 v[84:85], v[0:1], v[146:147], v[224:225] op_sel_hi:[0,1,1]
	v_pk_fma_f32 v[86:87], v[0:1], v[148:149], v[226:227] op_sel_hi:[0,1,1]
	v_pk_mul_f32 v[250:251], v[84:85], v[198:199]
	v_pk_fma_f32 v[236:237], v[84:85], v[194:195], v[236:237]
	v_pk_fma_f32 v[250:251], v[86:87], v[200:201], v[250:251]
	v_pk_mul_f32 v[186:187], v[84:85], v[150:151]
	v_add_f32_e32 v0, v250, v251
	v_pk_fma_f32 v[238:239], v[86:87], v[196:197], v[238:239]
	v_pk_fma_f32 v[186:187], v[86:87], v[152:153], v[186:187]
	v_add_f32_dpp v0, v0, v0 row_ror:8 row_mask:0xf bank_mask:0xf bound_ctrl:1
	s_waitcnt lgkmcnt(7)
	v_pk_mul_f32 v[108:109], v[108:109], v[242:243] op_sel_hi:[1,0]
	v_add_f32_e32 v218, v186, v187
	v_add_f32_dpp v0, v0, v0 row_ror:4 row_mask:0xf bank_mask:0xf bound_ctrl:1
	v_pk_mul_f32 v[110:111], v[110:111], v[242:243] op_sel_hi:[1,0]
	ds_read_b128 v[224:227], v96 offset:41088
	ds_read_b32 v214, v97 offset:40320
	ds_read_b128 v[142:145], v96 offset:40576
	v_add_f32_dpp v0, v0, v0 row_ror:2 row_mask:0xf bank_mask:0xf bound_ctrl:1
	ds_read_b128 v[138:141], v96 offset:40320
	ds_read_b128 v[146:149], v96 offset:40832
	ds_read_b128 v[150:153], v96 offset:41344
	v_add_f32_dpp v0, v0, v0 row_ror:1 row_mask:0xf bank_mask:0xf bound_ctrl:1
	v_pk_fma_f32 v[84:85], v[0:1], v[202:203], v[236:237] op_sel_hi:[0,1,1]
	v_pk_fma_f32 v[86:87], v[0:1], v[204:205], v[238:239] op_sel_hi:[0,1,1]
	v_pk_mul_f32 v[250:251], v[84:85], v[14:15]
	v_pk_fma_f32 v[108:109], v[84:85], v[10:11], v[108:109]
	v_pk_fma_f32 v[250:251], v[86:87], v[16:17], v[250:251]
	v_pk_mul_f32 v[186:187], v[84:85], v[206:207]
	v_add_f32_e32 v0, v250, v251
	v_pk_fma_f32 v[110:111], v[86:87], v[12:13], v[110:111]
	v_pk_fma_f32 v[186:187], v[86:87], v[208:209], v[186:187]
	v_add_f32_dpp v0, v0, v0 row_ror:8 row_mask:0xf bank_mask:0xf bound_ctrl:1
	s_waitcnt lgkmcnt(6)
	v_pk_mul_f32 v[220:221], v[220:221], v[246:247] op_sel_hi:[1,0]
	v_add_f32_e32 v219, v186, v187
	v_add_f32_dpp v0, v0, v0 row_ror:4 row_mask:0xf bank_mask:0xf bound_ctrl:1
	v_pk_mul_f32 v[222:223], v[222:223], v[246:247] op_sel_hi:[1,0]
	ds_write2st64_b32 v98, v218, v219 offset0:104 offset1:108
	ds_read_b128 v[236:239], v96 offset:42432
	ds_read_b32 v234, v97 offset:41664
	ds_read_b128 v[198:201], v96 offset:41920
	v_add_f32_dpp v0, v0, v0 row_ror:2 row_mask:0xf bank_mask:0xf bound_ctrl:1
	ds_read_b128 v[194:197], v96 offset:41664
	ds_read_b128 v[202:205], v96 offset:42176
	ds_read_b128 v[206:209], v96 offset:42688
	v_add_f32_dpp v0, v0, v0 row_ror:1 row_mask:0xf bank_mask:0xf bound_ctrl:1
	v_pk_fma_f32 v[84:85], v[0:1], v[18:19], v[108:109] op_sel_hi:[0,1,1]
	v_pk_fma_f32 v[86:87], v[0:1], v[20:21], v[110:111] op_sel_hi:[0,1,1]
	v_pk_mul_f32 v[250:251], v[84:85], v[122:123]
	v_pk_fma_f32 v[220:221], v[84:85], v[118:119], v[220:221]
	v_pk_fma_f32 v[250:251], v[86:87], v[124:125], v[250:251]
	v_pk_mul_f32 v[186:187], v[84:85], v[22:23]
	v_add_f32_e32 v0, v250, v251
	v_pk_fma_f32 v[222:223], v[86:87], v[120:121], v[222:223]
	v_pk_fma_f32 v[186:187], v[86:87], v[24:25], v[186:187]
	v_add_f32_dpp v0, v0, v0 row_ror:8 row_mask:0xf bank_mask:0xf bound_ctrl:1
	s_waitcnt lgkmcnt(7)
	v_pk_mul_f32 v[224:225], v[224:225], v[214:215] op_sel_hi:[1,0]
	v_add_f32_e32 v218, v186, v187
	v_add_f32_dpp v0, v0, v0 row_ror:4 row_mask:0xf bank_mask:0xf bound_ctrl:1
	v_pk_mul_f32 v[226:227], v[226:227], v[214:215] op_sel_hi:[1,0]
	s_nop 0
	v_add_f32_dpp v0, v0, v0 row_ror:2 row_mask:0xf bank_mask:0xf bound_ctrl:1
	s_nop 1
	v_add_f32_dpp v0, v0, v0 row_ror:1 row_mask:0xf bank_mask:0xf bound_ctrl:1
	v_pk_fma_f32 v[84:85], v[0:1], v[134:135], v[220:221] op_sel_hi:[0,1,1]
	v_pk_fma_f32 v[86:87], v[0:1], v[136:137], v[222:223] op_sel_hi:[0,1,1]
	v_pk_mul_f32 v[250:251], v[84:85], v[142:143]
	v_pk_fma_f32 v[224:225], v[84:85], v[138:139], v[224:225]
	v_pk_fma_f32 v[250:251], v[86:87], v[144:145], v[250:251]
	v_pk_mul_f32 v[186:187], v[84:85], v[230:231]
	v_add_f32_e32 v0, v250, v251
	v_pk_fma_f32 v[226:227], v[86:87], v[140:141], v[226:227]
	v_pk_fma_f32 v[186:187], v[86:87], v[232:233], v[186:187]
	v_add_f32_dpp v0, v0, v0 row_ror:8 row_mask:0xf bank_mask:0xf bound_ctrl:1
	s_waitcnt lgkmcnt(0)
	v_pk_mul_f32 v[236:237], v[236:237], v[234:235] op_sel_hi:[1,0]
	v_add_f32_e32 v219, v186, v187
	v_add_f32_dpp v0, v0, v0 row_ror:4 row_mask:0xf bank_mask:0xf bound_ctrl:1
	v_pk_mul_f32 v[238:239], v[238:239], v[234:235] op_sel_hi:[1,0]
	ds_write2st64_b32 v98, v218, v219 offset0:112 offset1:116
	v_add_f32_dpp v0, v0, v0 row_ror:2 row_mask:0xf bank_mask:0xf bound_ctrl:1
	s_nop 1
	v_add_f32_dpp v0, v0, v0 row_ror:1 row_mask:0xf bank_mask:0xf bound_ctrl:1
	v_pk_fma_f32 v[84:85], v[0:1], v[146:147], v[224:225] op_sel_hi:[0,1,1]
	v_pk_fma_f32 v[86:87], v[0:1], v[148:149], v[226:227] op_sel_hi:[0,1,1]
	v_pk_mul_f32 v[250:251], v[84:85], v[198:199]
	v_pk_fma_f32 v[236:237], v[84:85], v[194:195], v[236:237]
	v_pk_fma_f32 v[250:251], v[86:87], v[200:201], v[250:251]
	v_pk_mul_f32 v[186:187], v[84:85], v[150:151]
	v_add_f32_e32 v0, v250, v251
	v_pk_fma_f32 v[238:239], v[86:87], v[196:197], v[238:239]
	v_pk_fma_f32 v[186:187], v[86:87], v[152:153], v[186:187]
	v_add_f32_dpp v0, v0, v0 row_ror:8 row_mask:0xf bank_mask:0xf bound_ctrl:1
	v_add_f32_e32 v218, v186, v187
	s_nop 0
	v_add_f32_dpp v0, v0, v0 row_ror:4 row_mask:0xf bank_mask:0xf bound_ctrl:1
	s_nop 1
	v_add_f32_dpp v0, v0, v0 row_ror:2 row_mask:0xf bank_mask:0xf bound_ctrl:1
	s_nop 1
	v_add_f32_dpp v0, v0, v0 row_ror:1 row_mask:0xf bank_mask:0xf bound_ctrl:1
	v_pk_fma_f32 v[84:85], v[0:1], v[202:203], v[236:237] op_sel_hi:[0,1,1]
	v_pk_fma_f32 v[86:87], v[0:1], v[204:205], v[238:239] op_sel_hi:[0,1,1]
	v_pk_mul_f32 v[186:187], v[84:85], v[206:207]
	s_nop 0
	v_pk_fma_f32 v[186:187], v[86:87], v[208:209], v[186:187]
	s_nop 0
	v_add_f32_e32 v219, v186, v187
	ds_write2st64_b32 v98, v218, v219 offset0:120 offset1:124
